# K-loops: s_setprio 1 issued before the MMA-start barrier instead of after it, mid-burst priority flip removed: MMA section is 32 bare MFMAs between barriers; on top of R2
# speedup vs baseline: 1.0188x; 1.0022x over previous
.LBB0_904:
	s_add_i32 s69, s8, 2
	s_add_u32 s0, s52, 0xfff80080
	s_addc_u32 s1, s53, -1
	s_add_i32 s70, 0, 0x10000
	s_cmp_eq_u32 s66, s8
	s_cselect_b32 s59, s41, s1
	s_cselect_b32 s58, s45, s0
	s_cselect_b32 s9, s43, s68
	s_cselect_b32 s8, s65, s67
	s_add_i32 s0, 0, 0x14000
	v_add_u32_e32 v156, s70, v141
	v_add_u32_e32 v172, s0, v141
	ds_read_b128 v[144:147], v156
	ds_read_b128 v[148:151], v156 offset:1024
	ds_read_b128 v[152:155], v156 offset:2048
	ds_read_b128 v[156:159], v156 offset:3072
	ds_read_b128 v[160:163], v172
	ds_read_b128 v[164:167], v172 offset:1024
	ds_read_b128 v[168:171], v172 offset:2048
	ds_read_b128 v[172:175], v172 offset:3072
	v_lshl_add_u64 v[214:215], s[52:53], 0, v[138:139]
	s_add_i32 m0, s27, 0xc000
	ds_read_b128 v[176:179], v143
	ds_read_b128 v[180:183], v143 offset:1024
	ds_read_b128 v[184:187], v143 offset:2048
	ds_read_b128 v[188:191], v143 offset:3072
	ds_read_b128 v[192:195], v143 offset:4096
	ds_read_b128 v[202:205], v143 offset:5120
	ds_read_b128 v[206:209], v143 offset:6144
	ds_read_b128 v[210:213], v143 offset:7168
	global_load_lds_dwordx4 v[214:215], off
	v_lshl_add_u64 v[214:215], s[52:53], 0, v[136:137]
	s_add_i32 m0, s27, 0xe000
	s_nop 0
	global_load_lds_dwordx4 v[214:215], off
	s_waitcnt vmcnt(8)
	s_waitcnt lgkmcnt(0)
	s_setprio 1
	s_barrier
	v_mfma_f32_16x16x32_bf16 v[126:129], v[144:147], v[176:179], v[126:129]
	v_mfma_f32_16x16x32_bf16 v[118:121], v[152:155], v[176:179], v[118:121]
	v_mfma_f32_16x16x32_bf16 v[110:113], v[144:147], v[184:187], v[110:113]
	v_mfma_f32_16x16x32_bf16 v[102:105], v[152:155], v[184:187], v[102:105]
	v_mfma_f32_16x16x32_bf16 v[94:97], v[144:147], v[192:195], v[94:97]
	v_mfma_f32_16x16x32_bf16 v[86:89], v[152:155], v[192:195], v[86:89]
	v_mfma_f32_16x16x32_bf16 v[78:81], v[144:147], v[206:209], v[78:81]
	v_mfma_f32_16x16x32_bf16 v[70:73], v[152:155], v[206:209], v[70:73]
	v_mfma_f32_16x16x32_bf16 v[126:129], v[148:151], v[180:183], v[126:129]
	v_mfma_f32_16x16x32_bf16 v[118:121], v[156:159], v[180:183], v[118:121]
	v_mfma_f32_16x16x32_bf16 v[110:113], v[148:151], v[188:191], v[110:113]
	v_mfma_f32_16x16x32_bf16 v[102:105], v[156:159], v[188:191], v[102:105]
	v_mfma_f32_16x16x32_bf16 v[94:97], v[148:151], v[202:205], v[94:97]
	v_mfma_f32_16x16x32_bf16 v[86:89], v[156:159], v[202:205], v[86:89]
	v_mfma_f32_16x16x32_bf16 v[78:81], v[148:151], v[210:213], v[78:81]
	v_mfma_f32_16x16x32_bf16 v[70:73], v[156:159], v[210:213], v[70:73]
	v_mfma_f32_16x16x32_bf16 v[122:125], v[160:163], v[176:179], v[122:125]
	v_mfma_f32_16x16x32_bf16 v[114:117], v[168:171], v[176:179], v[114:117]
	v_mfma_f32_16x16x32_bf16 v[106:109], v[160:163], v[184:187], v[106:109]
	v_mfma_f32_16x16x32_bf16 v[98:101], v[168:171], v[184:187], v[98:101]
	v_mfma_f32_16x16x32_bf16 v[90:93], v[160:163], v[192:195], v[90:93]
	v_mfma_f32_16x16x32_bf16 v[82:85], v[168:171], v[192:195], v[82:85]
	v_mfma_f32_16x16x32_bf16 v[74:77], v[160:163], v[206:209], v[74:77]
	v_mfma_f32_16x16x32_bf16 v[66:69], v[168:171], v[206:209], v[66:69]
	v_mfma_f32_16x16x32_bf16 v[122:125], v[164:167], v[180:183], v[122:125]
	v_mfma_f32_16x16x32_bf16 v[114:117], v[172:175], v[180:183], v[114:117]
	v_mfma_f32_16x16x32_bf16 v[106:109], v[164:167], v[188:191], v[106:109]
	v_mfma_f32_16x16x32_bf16 v[98:101], v[172:175], v[188:191], v[98:101]
	v_mfma_f32_16x16x32_bf16 v[90:93], v[164:167], v[202:205], v[90:93]
	v_mfma_f32_16x16x32_bf16 v[82:85], v[172:175], v[202:205], v[82:85]
	v_mfma_f32_16x16x32_bf16 v[74:77], v[164:167], v[210:213], v[74:77]
	v_mfma_f32_16x16x32_bf16 v[66:69], v[172:175], v[210:213], v[66:69]
	s_barrier
	s_setprio 0
	s_add_i32 s1, s70, s26
	v_lshl_add_u64 v[214:215], s[8:9], 0, v[196:197]
	s_mov_b32 m0, s1
	ds_read_b128 v[176:179], v143 offset:16384
	ds_read_b128 v[180:183], v143 offset:17408
	ds_read_b128 v[184:187], v143 offset:18432
	ds_read_b128 v[188:191], v143 offset:19456
	ds_read_b128 v[192:195], v143 offset:20480
	ds_read_b128 v[202:205], v143 offset:21504
	ds_read_b128 v[206:209], v143 offset:22528
	ds_read_b128 v[210:213], v143 offset:23552
	global_load_lds_dwordx4 v[214:215], off
	s_add_i32 m0, s1, 0x2000
	s_add_u32 s70, s8, 0x80000
	v_lshl_add_u64 v[216:217], s[8:9], 0, v[130:131]
	s_addc_u32 s71, s9, 0
	s_add_i32 s0, s0, s26
	global_load_lds_dwordx4 v[216:217], off
	v_lshl_add_u64 v[218:219], s[70:71], 0, v[196:197]
	s_mov_b32 m0, s0
	v_lshl_add_u64 v[220:221], s[58:59], 0, v[132:133]
	global_load_lds_dwordx4 v[218:219], off
	v_lshl_add_u64 v[218:219], s[70:71], 0, v[130:131]
	s_add_i32 m0, s0, 0x2000
	s_nop 0
	global_load_lds_dwordx4 v[218:219], off
	v_lshl_add_u64 v[218:219], s[58:59], 0, v[134:135]
	s_mov_b32 m0, s27
	s_nop 0
	global_load_lds_dwordx4 v[218:219], off
	s_mov_b32 m0, s28
	s_nop 0
	global_load_lds_dwordx4 v[220:221], off
	s_waitcnt vmcnt(8)
	s_waitcnt lgkmcnt(0)
	s_setprio 1
	s_barrier
	v_mfma_f32_16x16x32_bf16 v[62:65], v[144:147], v[176:179], v[62:65]
	v_mfma_f32_16x16x32_bf16 v[54:57], v[152:155], v[176:179], v[54:57]
	v_mfma_f32_16x16x32_bf16 v[46:49], v[144:147], v[184:187], v[46:49]
	v_mfma_f32_16x16x32_bf16 v[38:41], v[152:155], v[184:187], v[38:41]
	v_mfma_f32_16x16x32_bf16 v[30:33], v[144:147], v[192:195], v[30:33]
	v_mfma_f32_16x16x32_bf16 v[22:25], v[152:155], v[192:195], v[22:25]
	v_mfma_f32_16x16x32_bf16 v[14:17], v[144:147], v[206:209], v[14:17]
	v_mfma_f32_16x16x32_bf16 v[6:9], v[152:155], v[206:209], v[6:9]
	v_mfma_f32_16x16x32_bf16 v[62:65], v[148:151], v[180:183], v[62:65]
	v_mfma_f32_16x16x32_bf16 v[54:57], v[156:159], v[180:183], v[54:57]
	v_mfma_f32_16x16x32_bf16 v[46:49], v[148:151], v[188:191], v[46:49]
	v_mfma_f32_16x16x32_bf16 v[38:41], v[156:159], v[188:191], v[38:41]
	v_mfma_f32_16x16x32_bf16 v[30:33], v[148:151], v[202:205], v[30:33]
	v_mfma_f32_16x16x32_bf16 v[22:25], v[156:159], v[202:205], v[22:25]
	v_mfma_f32_16x16x32_bf16 v[14:17], v[148:151], v[210:213], v[14:17]
	v_mfma_f32_16x16x32_bf16 v[6:9], v[156:159], v[210:213], v[6:9]
	v_mfma_f32_16x16x32_bf16 v[58:61], v[160:163], v[176:179], v[58:61]
	v_mfma_f32_16x16x32_bf16 v[50:53], v[168:171], v[176:179], v[50:53]
	v_mfma_f32_16x16x32_bf16 v[42:45], v[160:163], v[184:187], v[42:45]
	v_mfma_f32_16x16x32_bf16 v[34:37], v[168:171], v[184:187], v[34:37]
	v_mfma_f32_16x16x32_bf16 v[26:29], v[160:163], v[192:195], v[26:29]
	v_mfma_f32_16x16x32_bf16 v[18:21], v[168:171], v[192:195], v[18:21]
	v_mfma_f32_16x16x32_bf16 v[10:13], v[160:163], v[206:209], v[10:13]
	v_mfma_f32_16x16x32_bf16 v[2:5], v[168:171], v[206:209], v[2:5]
	v_mfma_f32_16x16x32_bf16 v[58:61], v[164:167], v[180:183], v[58:61]
	v_mfma_f32_16x16x32_bf16 v[50:53], v[172:175], v[180:183], v[50:53]
	v_mfma_f32_16x16x32_bf16 v[42:45], v[164:167], v[188:191], v[42:45]
	v_mfma_f32_16x16x32_bf16 v[34:37], v[172:175], v[188:191], v[34:37]
	v_mfma_f32_16x16x32_bf16 v[26:29], v[164:167], v[202:205], v[26:29]
	v_mfma_f32_16x16x32_bf16 v[18:21], v[172:175], v[202:205], v[18:21]
	v_mfma_f32_16x16x32_bf16 v[10:13], v[164:167], v[210:213], v[10:13]
	v_mfma_f32_16x16x32_bf16 v[2:5], v[172:175], v[210:213], v[2:5]
	s_barrier
	s_setprio 0
	s_add_i32 s0, 0, 0x18000
	s_add_i32 s1, 0, 0x1c000
	v_add_u32_e32 v156, s0, v141
	v_add_u32_e32 v172, s1, v141
	ds_read_b128 v[144:147], v156
	ds_read_b128 v[148:151], v156 offset:1024
	ds_read_b128 v[152:155], v156 offset:2048
	ds_read_b128 v[156:159], v156 offset:3072
	ds_read_b128 v[160:163], v172
	ds_read_b128 v[164:167], v172 offset:1024
	ds_read_b128 v[168:171], v172 offset:2048
	ds_read_b128 v[172:175], v172 offset:3072
	s_add_u32 s58, s58, 0x80000
	s_addc_u32 s59, s59, 0
	s_mov_b32 m0, s29
	v_lshl_add_u64 v[222:223], s[58:59], 0, v[134:135]
	ds_read_b128 v[176:179], v143 offset:32768
	ds_read_b128 v[180:183], v143 offset:33792
	ds_read_b128 v[184:187], v143 offset:34816
	ds_read_b128 v[188:191], v143 offset:35840
	ds_read_b128 v[192:195], v143 offset:36864
	ds_read_b128 v[202:205], v143 offset:37888
	ds_read_b128 v[206:209], v143 offset:38912
	ds_read_b128 v[210:213], v143 offset:39936
	global_load_lds_dwordx4 v[222:223], off
	v_lshl_add_u64 v[222:223], s[58:59], 0, v[132:133]
	s_mov_b32 m0, s30
	s_nop 0
	global_load_lds_dwordx4 v[222:223], off
	s_waitcnt vmcnt(8)
	s_waitcnt lgkmcnt(0)
	s_setprio 1
	s_barrier
	v_mfma_f32_16x16x32_bf16 v[126:129], v[144:147], v[176:179], v[126:129]
	v_mfma_f32_16x16x32_bf16 v[118:121], v[152:155], v[176:179], v[118:121]
	v_mfma_f32_16x16x32_bf16 v[110:113], v[144:147], v[184:187], v[110:113]
	v_mfma_f32_16x16x32_bf16 v[102:105], v[152:155], v[184:187], v[102:105]
	v_mfma_f32_16x16x32_bf16 v[94:97], v[144:147], v[192:195], v[94:97]
	v_mfma_f32_16x16x32_bf16 v[86:89], v[152:155], v[192:195], v[86:89]
	v_mfma_f32_16x16x32_bf16 v[78:81], v[144:147], v[206:209], v[78:81]
	v_mfma_f32_16x16x32_bf16 v[70:73], v[152:155], v[206:209], v[70:73]
	v_mfma_f32_16x16x32_bf16 v[126:129], v[148:151], v[180:183], v[126:129]
	v_mfma_f32_16x16x32_bf16 v[118:121], v[156:159], v[180:183], v[118:121]
	v_mfma_f32_16x16x32_bf16 v[110:113], v[148:151], v[188:191], v[110:113]
	v_mfma_f32_16x16x32_bf16 v[102:105], v[156:159], v[188:191], v[102:105]
	v_mfma_f32_16x16x32_bf16 v[94:97], v[148:151], v[202:205], v[94:97]
	v_mfma_f32_16x16x32_bf16 v[86:89], v[156:159], v[202:205], v[86:89]
	v_mfma_f32_16x16x32_bf16 v[78:81], v[148:151], v[210:213], v[78:81]
	v_mfma_f32_16x16x32_bf16 v[70:73], v[156:159], v[210:213], v[70:73]
	v_mfma_f32_16x16x32_bf16 v[122:125], v[160:163], v[176:179], v[122:125]
	v_mfma_f32_16x16x32_bf16 v[114:117], v[168:171], v[176:179], v[114:117]
	v_mfma_f32_16x16x32_bf16 v[106:109], v[160:163], v[184:187], v[106:109]
	v_mfma_f32_16x16x32_bf16 v[98:101], v[168:171], v[184:187], v[98:101]
	v_mfma_f32_16x16x32_bf16 v[90:93], v[160:163], v[192:195], v[90:93]
	v_mfma_f32_16x16x32_bf16 v[82:85], v[168:171], v[192:195], v[82:85]
	v_mfma_f32_16x16x32_bf16 v[74:77], v[160:163], v[206:209], v[74:77]
	v_mfma_f32_16x16x32_bf16 v[66:69], v[168:171], v[206:209], v[66:69]
	v_mfma_f32_16x16x32_bf16 v[122:125], v[164:167], v[180:183], v[122:125]
	v_mfma_f32_16x16x32_bf16 v[114:117], v[172:175], v[180:183], v[114:117]
	v_mfma_f32_16x16x32_bf16 v[106:109], v[164:167], v[188:191], v[106:109]
	v_mfma_f32_16x16x32_bf16 v[98:101], v[172:175], v[188:191], v[98:101]
	v_mfma_f32_16x16x32_bf16 v[90:93], v[164:167], v[202:205], v[90:93]
	v_mfma_f32_16x16x32_bf16 v[82:85], v[172:175], v[202:205], v[82:85]
	v_mfma_f32_16x16x32_bf16 v[74:77], v[164:167], v[210:213], v[74:77]
	v_mfma_f32_16x16x32_bf16 v[66:69], v[172:175], v[210:213], v[66:69]
	s_barrier
	s_setprio 0
	s_add_i32 s0, s0, s26
	v_lshl_add_u64 v[214:215], v[214:215], 0, s[16:17]
	s_mov_b32 m0, s0
	ds_read_b128 v[176:179], v143 offset:49152
	ds_read_b128 v[180:183], v143 offset:50176
	ds_read_b128 v[184:187], v143 offset:51200
	ds_read_b128 v[188:191], v143 offset:52224
	ds_read_b128 v[192:195], v143 offset:53248
	ds_read_b128 v[202:205], v143 offset:54272
	ds_read_b128 v[206:209], v143 offset:55296
	ds_read_b128 v[210:213], v143 offset:56320
	global_load_lds_dwordx4 v[214:215], off
	s_add_i32 m0, s0, 0x2000
	s_add_u32 s8, s8, 0x80080
	v_lshl_add_u64 v[214:215], v[216:217], 0, s[16:17]
	s_addc_u32 s9, s9, 0
	s_add_i32 s0, s1, s26
	global_load_lds_dwordx4 v[214:215], off
	v_lshl_add_u64 v[214:215], s[8:9], 0, v[196:197]
	s_mov_b32 m0, s0
	s_nop 0
	global_load_lds_dwordx4 v[214:215], off
	v_lshl_add_u64 v[214:215], s[8:9], 0, v[130:131]
	s_add_i32 m0, s0, 0x2000
	s_nop 0
	global_load_lds_dwordx4 v[214:215], off
	v_lshl_add_u64 v[214:215], v[218:219], 0, s[16:17]
	s_mov_b32 m0, s31
	s_nop 0
	global_load_lds_dwordx4 v[214:215], off
	v_lshl_add_u64 v[214:215], v[220:221], 0, s[16:17]
	s_mov_b32 m0, s34
	s_nop 0
	global_load_lds_dwordx4 v[214:215], off
	s_waitcnt vmcnt(8)
	s_waitcnt lgkmcnt(0)
	s_setprio 1
	s_barrier
	v_mfma_f32_16x16x32_bf16 v[62:65], v[144:147], v[176:179], v[62:65]
	v_mfma_f32_16x16x32_bf16 v[54:57], v[152:155], v[176:179], v[54:57]
	v_mfma_f32_16x16x32_bf16 v[46:49], v[144:147], v[184:187], v[46:49]
	v_mfma_f32_16x16x32_bf16 v[38:41], v[152:155], v[184:187], v[38:41]
	v_mfma_f32_16x16x32_bf16 v[30:33], v[144:147], v[192:195], v[30:33]
	v_mfma_f32_16x16x32_bf16 v[22:25], v[152:155], v[192:195], v[22:25]
	v_mfma_f32_16x16x32_bf16 v[14:17], v[144:147], v[206:209], v[14:17]
	v_mfma_f32_16x16x32_bf16 v[6:9], v[152:155], v[206:209], v[6:9]
	v_mfma_f32_16x16x32_bf16 v[62:65], v[148:151], v[180:183], v[62:65]
	v_mfma_f32_16x16x32_bf16 v[54:57], v[156:159], v[180:183], v[54:57]
	v_mfma_f32_16x16x32_bf16 v[46:49], v[148:151], v[188:191], v[46:49]
	v_mfma_f32_16x16x32_bf16 v[38:41], v[156:159], v[188:191], v[38:41]
	v_mfma_f32_16x16x32_bf16 v[30:33], v[148:151], v[202:205], v[30:33]
	v_mfma_f32_16x16x32_bf16 v[22:25], v[156:159], v[202:205], v[22:25]
	v_mfma_f32_16x16x32_bf16 v[14:17], v[148:151], v[210:213], v[14:17]
	v_mfma_f32_16x16x32_bf16 v[6:9], v[156:159], v[210:213], v[6:9]
	v_mfma_f32_16x16x32_bf16 v[58:61], v[160:163], v[176:179], v[58:61]
	v_mfma_f32_16x16x32_bf16 v[50:53], v[168:171], v[176:179], v[50:53]
	v_mfma_f32_16x16x32_bf16 v[42:45], v[160:163], v[184:187], v[42:45]
	v_mfma_f32_16x16x32_bf16 v[34:37], v[168:171], v[184:187], v[34:37]
	v_mfma_f32_16x16x32_bf16 v[26:29], v[160:163], v[192:195], v[26:29]
	v_mfma_f32_16x16x32_bf16 v[18:21], v[168:171], v[192:195], v[18:21]
	v_mfma_f32_16x16x32_bf16 v[10:13], v[160:163], v[206:209], v[10:13]
	v_mfma_f32_16x16x32_bf16 v[2:5], v[168:171], v[206:209], v[2:5]
	v_mfma_f32_16x16x32_bf16 v[58:61], v[164:167], v[180:183], v[58:61]
	v_mfma_f32_16x16x32_bf16 v[50:53], v[172:175], v[180:183], v[50:53]
	v_mfma_f32_16x16x32_bf16 v[42:45], v[164:167], v[188:191], v[42:45]
	v_mfma_f32_16x16x32_bf16 v[34:37], v[172:175], v[188:191], v[34:37]
	v_mfma_f32_16x16x32_bf16 v[26:29], v[164:167], v[202:205], v[26:29]
	v_mfma_f32_16x16x32_bf16 v[18:21], v[172:175], v[202:205], v[18:21]
	v_mfma_f32_16x16x32_bf16 v[10:13], v[164:167], v[210:213], v[10:13]
	v_mfma_f32_16x16x32_bf16 v[2:5], v[172:175], v[210:213], v[2:5]
	s_barrier
	s_setprio 0
	s_add_u32 s67, s67, 0x100
	s_addc_u32 s68, s68, 0
	s_add_u32 s52, s52, 0x100
	s_addc_u32 s53, s53, 0
	s_cmp_ge_i32 s69, s62
	s_mov_b32 s8, s69
	s_cbranch_scc0 .LBB0_904
	s_and_b64 vcc, exec, s[38:39]
	s_cbranch_vccz .LBB0_907
	s_barrier

.LBB0_987:
	s_add_i32 s72, s50, 2
	s_add_u32 s8, s48, 0x100
	s_addc_u32 s9, s49, 0
	s_add_i32 s0, 0, 0x10000
	s_cmp_eq_u32 s41, s50
	s_cselect_b32 s53, s45, s9
	s_cselect_b32 s52, s44, s8
	s_cselect_b32 s51, s47, s71
	s_cselect_b32 s50, s46, s70
	s_add_i32 s1, 0, 0x14000
	v_add_u32_e32 v142, s0, v188
	v_add_u32_e32 v172, s1, v188
	ds_read_b128 v[130:133], v142
	ds_read_b128 v[134:137], v142 offset:1024
	ds_read_b128 v[138:141], v142 offset:2048
	ds_read_b128 v[142:145], v142 offset:3072
	ds_read_b128 v[146:149], v172
	ds_read_b128 v[164:167], v172 offset:1024
	ds_read_b128 v[168:171], v172 offset:2048
	ds_read_b128 v[172:175], v172 offset:3072
	v_lshl_add_u64 v[194:195], s[48:49], 0, v[162:163]
	s_add_i32 m0, s27, 0xc000
	ds_read_b128 v[176:179], v189
	ds_read_b128 v[180:183], v189 offset:1024
	ds_read_b128 v[184:187], v189 offset:2048
	ds_read_b128 v[190:193], v189 offset:3072
	ds_read_b128 v[202:205], v189 offset:4096
	ds_read_b128 v[206:209], v189 offset:5120
	ds_read_b128 v[210:213], v189 offset:6144
	ds_read_b128 v[214:217], v189 offset:7168
	global_load_lds_dwordx4 v[194:195], off
	v_lshl_add_u64 v[194:195], s[48:49], 0, v[160:161]
	s_add_i32 m0, s27, 0xe000
	s_nop 0
	global_load_lds_dwordx4 v[194:195], off
	s_waitcnt vmcnt(8)
	s_waitcnt lgkmcnt(0)
	s_setprio 1
	s_barrier
	v_mfma_f32_16x16x32_bf16 v[126:129], v[130:133], v[176:179], v[126:129]
	v_mfma_f32_16x16x32_bf16 v[122:125], v[138:141], v[176:179], v[122:125]
	v_mfma_f32_16x16x32_bf16 v[110:113], v[130:133], v[184:187], v[110:113]
	v_mfma_f32_16x16x32_bf16 v[106:109], v[138:141], v[184:187], v[106:109]
	v_mfma_f32_16x16x32_bf16 v[98:101], v[130:133], v[202:205], v[98:101]
	v_mfma_f32_16x16x32_bf16 v[90:93], v[138:141], v[202:205], v[90:93]
	v_mfma_f32_16x16x32_bf16 v[82:85], v[130:133], v[210:213], v[82:85]
	v_mfma_f32_16x16x32_bf16 v[74:77], v[138:141], v[210:213], v[74:77]
	v_mfma_f32_16x16x32_bf16 v[126:129], v[134:137], v[180:183], v[126:129]
	v_mfma_f32_16x16x32_bf16 v[122:125], v[142:145], v[180:183], v[122:125]
	v_mfma_f32_16x16x32_bf16 v[110:113], v[134:137], v[190:193], v[110:113]
	v_mfma_f32_16x16x32_bf16 v[106:109], v[142:145], v[190:193], v[106:109]
	v_mfma_f32_16x16x32_bf16 v[98:101], v[134:137], v[206:209], v[98:101]
	v_mfma_f32_16x16x32_bf16 v[90:93], v[142:145], v[206:209], v[90:93]
	v_mfma_f32_16x16x32_bf16 v[82:85], v[134:137], v[214:217], v[82:85]
	v_mfma_f32_16x16x32_bf16 v[74:77], v[142:145], v[214:217], v[74:77]
	v_mfma_f32_16x16x32_bf16 v[118:121], v[146:149], v[176:179], v[118:121]
	v_mfma_f32_16x16x32_bf16 v[114:117], v[168:171], v[176:179], v[114:117]
	v_mfma_f32_16x16x32_bf16 v[102:105], v[146:149], v[184:187], v[102:105]
	v_mfma_f32_16x16x32_bf16 v[94:97], v[168:171], v[184:187], v[94:97]
	v_mfma_f32_16x16x32_bf16 v[86:89], v[146:149], v[202:205], v[86:89]
	v_mfma_f32_16x16x32_bf16 v[78:81], v[168:171], v[202:205], v[78:81]
	v_mfma_f32_16x16x32_bf16 v[70:73], v[146:149], v[210:213], v[70:73]
	v_mfma_f32_16x16x32_bf16 v[66:69], v[168:171], v[210:213], v[66:69]
	v_mfma_f32_16x16x32_bf16 v[118:121], v[164:167], v[180:183], v[118:121]
	v_mfma_f32_16x16x32_bf16 v[114:117], v[172:175], v[180:183], v[114:117]
	v_mfma_f32_16x16x32_bf16 v[102:105], v[164:167], v[190:193], v[102:105]
	v_mfma_f32_16x16x32_bf16 v[94:97], v[172:175], v[190:193], v[94:97]
	v_mfma_f32_16x16x32_bf16 v[86:89], v[164:167], v[206:209], v[86:89]
	v_mfma_f32_16x16x32_bf16 v[78:81], v[172:175], v[206:209], v[78:81]
	v_mfma_f32_16x16x32_bf16 v[70:73], v[164:167], v[214:217], v[70:73]
	v_mfma_f32_16x16x32_bf16 v[66:69], v[172:175], v[214:217], v[66:69]
	s_barrier
	s_setprio 0
	s_add_i32 s0, s0, s26
	v_lshl_add_u64 v[194:195], s[50:51], 0, v[196:197]
	s_mov_b32 m0, s0
	ds_read_b128 v[176:179], v189 offset:16384
	ds_read_b128 v[180:183], v189 offset:17408
	ds_read_b128 v[184:187], v189 offset:18432
	ds_read_b128 v[190:193], v189 offset:19456
	ds_read_b128 v[202:205], v189 offset:20480
	ds_read_b128 v[206:209], v189 offset:21504
	ds_read_b128 v[210:213], v189 offset:22528
	ds_read_b128 v[214:217], v189 offset:23552
	global_load_lds_dwordx4 v[194:195], off
	s_add_i32 m0, s0, 0x2000
	s_add_u32 s48, s50, 0x158000
	v_lshl_add_u64 v[218:219], s[50:51], 0, v[154:155]
	s_addc_u32 s49, s51, 0
	s_add_i32 s0, s1, s26
	global_load_lds_dwordx4 v[218:219], off
	v_lshl_add_u64 v[220:221], s[48:49], 0, v[196:197]
	s_mov_b32 m0, s0
	v_lshl_add_u64 v[222:223], s[52:53], 0, v[152:153]
	global_load_lds_dwordx4 v[220:221], off
	v_lshl_add_u64 v[220:221], s[48:49], 0, v[154:155]
	s_add_i32 m0, s0, 0x2000
	s_nop 0
	global_load_lds_dwordx4 v[220:221], off
	v_lshl_add_u64 v[220:221], s[52:53], 0, v[150:151]
	s_mov_b32 m0, s27
	s_nop 0
	global_load_lds_dwordx4 v[220:221], off
	s_mov_b32 m0, s28
	s_nop 0
	global_load_lds_dwordx4 v[222:223], off
	s_waitcnt vmcnt(8)
	s_waitcnt lgkmcnt(0)
	s_setprio 1
	s_barrier
	v_mfma_f32_16x16x32_bf16 v[62:65], v[130:133], v[176:179], v[62:65]
	v_mfma_f32_16x16x32_bf16 v[58:61], v[138:141], v[176:179], v[58:61]
	v_mfma_f32_16x16x32_bf16 v[50:53], v[130:133], v[184:187], v[50:53]
	v_mfma_f32_16x16x32_bf16 v[42:45], v[138:141], v[184:187], v[42:45]
	v_mfma_f32_16x16x32_bf16 v[34:37], v[130:133], v[202:205], v[34:37]
	v_mfma_f32_16x16x32_bf16 v[26:29], v[138:141], v[202:205], v[26:29]
	v_mfma_f32_16x16x32_bf16 v[18:21], v[130:133], v[210:213], v[18:21]
	v_mfma_f32_16x16x32_bf16 v[10:13], v[138:141], v[210:213], v[10:13]
	v_mfma_f32_16x16x32_bf16 v[62:65], v[134:137], v[180:183], v[62:65]
	v_mfma_f32_16x16x32_bf16 v[58:61], v[142:145], v[180:183], v[58:61]
	v_mfma_f32_16x16x32_bf16 v[50:53], v[134:137], v[190:193], v[50:53]
	v_mfma_f32_16x16x32_bf16 v[42:45], v[142:145], v[190:193], v[42:45]
	v_mfma_f32_16x16x32_bf16 v[34:37], v[134:137], v[206:209], v[34:37]
	v_mfma_f32_16x16x32_bf16 v[26:29], v[142:145], v[206:209], v[26:29]
	v_mfma_f32_16x16x32_bf16 v[18:21], v[134:137], v[214:217], v[18:21]
	v_mfma_f32_16x16x32_bf16 v[10:13], v[142:145], v[214:217], v[10:13]
	v_mfma_f32_16x16x32_bf16 v[54:57], v[146:149], v[176:179], v[54:57]
	v_mfma_f32_16x16x32_bf16 v[46:49], v[168:171], v[176:179], v[46:49]
	v_mfma_f32_16x16x32_bf16 v[38:41], v[146:149], v[184:187], v[38:41]
	v_mfma_f32_16x16x32_bf16 v[30:33], v[168:171], v[184:187], v[30:33]
	v_mfma_f32_16x16x32_bf16 v[22:25], v[146:149], v[202:205], v[22:25]
	v_mfma_f32_16x16x32_bf16 v[14:17], v[168:171], v[202:205], v[14:17]
	v_mfma_f32_16x16x32_bf16 v[6:9], v[146:149], v[210:213], v[6:9]
	v_mfma_f32_16x16x32_bf16 v[2:5], v[168:171], v[210:213], v[2:5]
	v_mfma_f32_16x16x32_bf16 v[54:57], v[164:167], v[180:183], v[54:57]
	v_mfma_f32_16x16x32_bf16 v[46:49], v[172:175], v[180:183], v[46:49]
	v_mfma_f32_16x16x32_bf16 v[38:41], v[164:167], v[190:193], v[38:41]
	v_mfma_f32_16x16x32_bf16 v[30:33], v[172:175], v[190:193], v[30:33]
	v_mfma_f32_16x16x32_bf16 v[22:25], v[164:167], v[206:209], v[22:25]
	v_mfma_f32_16x16x32_bf16 v[14:17], v[172:175], v[206:209], v[14:17]
	v_mfma_f32_16x16x32_bf16 v[6:9], v[164:167], v[214:217], v[6:9]
	v_mfma_f32_16x16x32_bf16 v[2:5], v[172:175], v[214:217], v[2:5]
	s_barrier
	s_setprio 0
	s_add_i32 s0, 0, 0x18000
	s_add_i32 s1, 0, 0x1c000
	v_add_u32_e32 v142, s0, v188
	v_add_u32_e32 v172, s1, v188
	ds_read_b128 v[130:133], v142
	ds_read_b128 v[134:137], v142 offset:1024
	ds_read_b128 v[138:141], v142 offset:2048
	ds_read_b128 v[142:145], v142 offset:3072
	ds_read_b128 v[146:149], v172
	ds_read_b128 v[164:167], v172 offset:1024
	ds_read_b128 v[168:171], v172 offset:2048
	ds_read_b128 v[172:175], v172 offset:3072
	s_add_u32 s48, s52, 0x158000
	s_addc_u32 s49, s53, 0
	s_mov_b32 m0, s29
	v_lshl_add_u64 v[224:225], s[48:49], 0, v[150:151]
	ds_read_b128 v[176:179], v189 offset:32768
	ds_read_b128 v[180:183], v189 offset:33792
	ds_read_b128 v[184:187], v189 offset:34816
	ds_read_b128 v[190:193], v189 offset:35840
	ds_read_b128 v[202:205], v189 offset:36864
	ds_read_b128 v[206:209], v189 offset:37888
	ds_read_b128 v[210:213], v189 offset:38912
	ds_read_b128 v[214:217], v189 offset:39936
	global_load_lds_dwordx4 v[224:225], off
	v_lshl_add_u64 v[224:225], s[48:49], 0, v[152:153]
	s_mov_b32 m0, s30
	s_nop 0
	global_load_lds_dwordx4 v[224:225], off
	s_waitcnt vmcnt(8)
	s_waitcnt lgkmcnt(0)
	s_setprio 1
	s_barrier
	v_mfma_f32_16x16x32_bf16 v[126:129], v[130:133], v[176:179], v[126:129]
	v_mfma_f32_16x16x32_bf16 v[122:125], v[138:141], v[176:179], v[122:125]
	v_mfma_f32_16x16x32_bf16 v[110:113], v[130:133], v[184:187], v[110:113]
	v_mfma_f32_16x16x32_bf16 v[106:109], v[138:141], v[184:187], v[106:109]
	v_mfma_f32_16x16x32_bf16 v[98:101], v[130:133], v[202:205], v[98:101]
	v_mfma_f32_16x16x32_bf16 v[90:93], v[138:141], v[202:205], v[90:93]
	v_mfma_f32_16x16x32_bf16 v[82:85], v[130:133], v[210:213], v[82:85]
	v_mfma_f32_16x16x32_bf16 v[74:77], v[138:141], v[210:213], v[74:77]
	v_mfma_f32_16x16x32_bf16 v[126:129], v[134:137], v[180:183], v[126:129]
	v_mfma_f32_16x16x32_bf16 v[122:125], v[142:145], v[180:183], v[122:125]
	v_mfma_f32_16x16x32_bf16 v[110:113], v[134:137], v[190:193], v[110:113]
	v_mfma_f32_16x16x32_bf16 v[106:109], v[142:145], v[190:193], v[106:109]
	v_mfma_f32_16x16x32_bf16 v[98:101], v[134:137], v[206:209], v[98:101]
	v_mfma_f32_16x16x32_bf16 v[90:93], v[142:145], v[206:209], v[90:93]
	v_mfma_f32_16x16x32_bf16 v[82:85], v[134:137], v[214:217], v[82:85]
	v_mfma_f32_16x16x32_bf16 v[74:77], v[142:145], v[214:217], v[74:77]
	v_mfma_f32_16x16x32_bf16 v[118:121], v[146:149], v[176:179], v[118:121]
	v_mfma_f32_16x16x32_bf16 v[114:117], v[168:171], v[176:179], v[114:117]
	v_mfma_f32_16x16x32_bf16 v[102:105], v[146:149], v[184:187], v[102:105]
	v_mfma_f32_16x16x32_bf16 v[94:97], v[168:171], v[184:187], v[94:97]
	v_mfma_f32_16x16x32_bf16 v[86:89], v[146:149], v[202:205], v[86:89]
	v_mfma_f32_16x16x32_bf16 v[78:81], v[168:171], v[202:205], v[78:81]
	v_mfma_f32_16x16x32_bf16 v[70:73], v[146:149], v[210:213], v[70:73]
	v_mfma_f32_16x16x32_bf16 v[66:69], v[168:171], v[210:213], v[66:69]
	v_mfma_f32_16x16x32_bf16 v[118:121], v[164:167], v[180:183], v[118:121]
	v_mfma_f32_16x16x32_bf16 v[114:117], v[172:175], v[180:183], v[114:117]
	v_mfma_f32_16x16x32_bf16 v[102:105], v[164:167], v[190:193], v[102:105]
	v_mfma_f32_16x16x32_bf16 v[94:97], v[172:175], v[190:193], v[94:97]
	v_mfma_f32_16x16x32_bf16 v[86:89], v[164:167], v[206:209], v[86:89]
	v_mfma_f32_16x16x32_bf16 v[78:81], v[172:175], v[206:209], v[78:81]
	v_mfma_f32_16x16x32_bf16 v[70:73], v[164:167], v[214:217], v[70:73]
	v_mfma_f32_16x16x32_bf16 v[66:69], v[172:175], v[214:217], v[66:69]
	s_barrier
	s_setprio 0
	s_add_i32 s0, s0, s26
	v_lshl_add_u64 v[194:195], v[194:195], 0, s[16:17]
	s_mov_b32 m0, s0
	ds_read_b128 v[176:179], v189 offset:49152
	ds_read_b128 v[180:183], v189 offset:50176
	ds_read_b128 v[184:187], v189 offset:51200
	ds_read_b128 v[190:193], v189 offset:52224
	ds_read_b128 v[202:205], v189 offset:53248
	ds_read_b128 v[206:209], v189 offset:54272
	ds_read_b128 v[210:213], v189 offset:55296
	ds_read_b128 v[214:217], v189 offset:56320
	global_load_lds_dwordx4 v[194:195], off
	s_add_i32 m0, s0, 0x2000
	s_add_u32 s48, s50, 0x158080
	v_lshl_add_u64 v[194:195], v[218:219], 0, s[16:17]
	s_addc_u32 s49, s51, 0
	s_add_i32 s0, s1, s26
	global_load_lds_dwordx4 v[194:195], off
	v_lshl_add_u64 v[194:195], s[48:49], 0, v[196:197]
	s_mov_b32 m0, s0
	s_nop 0
	global_load_lds_dwordx4 v[194:195], off
	v_lshl_add_u64 v[194:195], s[48:49], 0, v[154:155]
	s_add_i32 m0, s0, 0x2000
	s_nop 0
	global_load_lds_dwordx4 v[194:195], off
	v_lshl_add_u64 v[194:195], v[220:221], 0, s[16:17]
	s_mov_b32 m0, s35
	s_nop 0
	global_load_lds_dwordx4 v[194:195], off
	v_lshl_add_u64 v[194:195], v[222:223], 0, s[16:17]
	s_mov_b32 m0, s58
	s_nop 0
	global_load_lds_dwordx4 v[194:195], off
	s_waitcnt vmcnt(8)
	s_waitcnt lgkmcnt(0)
	s_setprio 1
	s_barrier
	v_mfma_f32_16x16x32_bf16 v[62:65], v[130:133], v[176:179], v[62:65]
	v_mfma_f32_16x16x32_bf16 v[58:61], v[138:141], v[176:179], v[58:61]
	v_mfma_f32_16x16x32_bf16 v[50:53], v[130:133], v[184:187], v[50:53]
	v_mfma_f32_16x16x32_bf16 v[42:45], v[138:141], v[184:187], v[42:45]
	v_mfma_f32_16x16x32_bf16 v[34:37], v[130:133], v[202:205], v[34:37]
	v_mfma_f32_16x16x32_bf16 v[26:29], v[138:141], v[202:205], v[26:29]
	v_mfma_f32_16x16x32_bf16 v[18:21], v[130:133], v[210:213], v[18:21]
	v_mfma_f32_16x16x32_bf16 v[10:13], v[138:141], v[210:213], v[10:13]
	v_mfma_f32_16x16x32_bf16 v[62:65], v[134:137], v[180:183], v[62:65]
	v_mfma_f32_16x16x32_bf16 v[58:61], v[142:145], v[180:183], v[58:61]
	v_mfma_f32_16x16x32_bf16 v[50:53], v[134:137], v[190:193], v[50:53]
	v_mfma_f32_16x16x32_bf16 v[42:45], v[142:145], v[190:193], v[42:45]
	v_mfma_f32_16x16x32_bf16 v[34:37], v[134:137], v[206:209], v[34:37]
	v_mfma_f32_16x16x32_bf16 v[26:29], v[142:145], v[206:209], v[26:29]
	v_mfma_f32_16x16x32_bf16 v[18:21], v[134:137], v[214:217], v[18:21]
	v_mfma_f32_16x16x32_bf16 v[10:13], v[142:145], v[214:217], v[10:13]
	v_mfma_f32_16x16x32_bf16 v[54:57], v[146:149], v[176:179], v[54:57]
	v_mfma_f32_16x16x32_bf16 v[46:49], v[168:171], v[176:179], v[46:49]
	v_mfma_f32_16x16x32_bf16 v[38:41], v[146:149], v[184:187], v[38:41]
	v_mfma_f32_16x16x32_bf16 v[30:33], v[168:171], v[184:187], v[30:33]
	v_mfma_f32_16x16x32_bf16 v[22:25], v[146:149], v[202:205], v[22:25]
	v_mfma_f32_16x16x32_bf16 v[14:17], v[168:171], v[202:205], v[14:17]
	v_mfma_f32_16x16x32_bf16 v[6:9], v[146:149], v[210:213], v[6:9]
	v_mfma_f32_16x16x32_bf16 v[2:5], v[168:171], v[210:213], v[2:5]
	v_mfma_f32_16x16x32_bf16 v[54:57], v[164:167], v[180:183], v[54:57]
	v_mfma_f32_16x16x32_bf16 v[46:49], v[172:175], v[180:183], v[46:49]
	v_mfma_f32_16x16x32_bf16 v[38:41], v[164:167], v[190:193], v[38:41]
	v_mfma_f32_16x16x32_bf16 v[30:33], v[172:175], v[190:193], v[30:33]
	v_mfma_f32_16x16x32_bf16 v[22:25], v[164:167], v[206:209], v[22:25]
	v_mfma_f32_16x16x32_bf16 v[14:17], v[172:175], v[206:209], v[14:17]
	v_mfma_f32_16x16x32_bf16 v[6:9], v[164:167], v[214:217], v[6:9]
	v_mfma_f32_16x16x32_bf16 v[2:5], v[172:175], v[214:217], v[2:5]
	s_barrier
	s_setprio 0
	s_add_u32 s70, s70, 0x100
	s_addc_u32 s71, s71, 0
	s_cmp_ge_i32 s72, s69
	s_mov_b64 s[48:49], s[8:9]
	s_mov_b32 s50, s72
	s_cbranch_scc0 .LBB0_987
	s_and_b64 vcc, exec, s[38:39]
	s_cbranch_vccz .LBB0_990
	s_barrier

.LBB0_1135:
	s_add_i32 s71, s8, 2
	s_add_u32 s0, s58, 0xfff80080
	s_addc_u32 s1, s59, -1
	s_add_i32 s72, 0, 0x10000
	s_cmp_eq_u32 s68, s8
	s_cselect_b32 s63, s43, s1
	s_cselect_b32 s62, s47, s0
	v_add_u32_e32 v146, s72, v149
	s_cselect_b32 s9, s45, s70
	s_cselect_b32 s8, s67, s69
	s_add_i32 s0, 0, 0x14000
	ds_read_b128 v[142:145], v146
	ds_read_b128 v[152:155], v146 offset:1024
	ds_read_b128 v[156:159], v146 offset:2048
	ds_read_b128 v[160:163], v146 offset:3072
	v_add_u32_e32 v146, s0, v149
	ds_read_b128 v[164:167], v146
	ds_read_b128 v[168:171], v146 offset:1024
	ds_read_b128 v[172:175], v146 offset:2048
	ds_read_b128 v[176:179], v146 offset:3072
	v_lshl_add_u64 v[146:147], s[58:59], 0, v[140:141]
	s_add_i32 m0, s27, 0xc000
	ds_read_b128 v[180:183], v151
	ds_read_b128 v[184:187], v151 offset:1024
	ds_read_b128 v[188:191], v151 offset:2048
	ds_read_b128 v[192:195], v151 offset:3072
	ds_read_b128 v[202:205], v151 offset:4096
	ds_read_b128 v[206:209], v151 offset:5120
	ds_read_b128 v[210:213], v151 offset:6144
	ds_read_b128 v[214:217], v151 offset:7168
	global_load_lds_dwordx4 v[146:147], off
	v_lshl_add_u64 v[146:147], s[58:59], 0, v[138:139]
	s_add_i32 m0, s27, 0xe000
	s_nop 0
	global_load_lds_dwordx4 v[146:147], off
	s_waitcnt vmcnt(8)
	s_waitcnt lgkmcnt(0)
	s_setprio 1
	s_barrier
	v_mfma_f32_16x16x32_bf16 v[126:129], v[142:145], v[180:183], v[126:129]
	v_mfma_f32_16x16x32_bf16 v[122:125], v[156:159], v[180:183], v[122:125]
	v_mfma_f32_16x16x32_bf16 v[118:121], v[142:145], v[188:191], v[118:121]
	v_mfma_f32_16x16x32_bf16 v[110:113], v[156:159], v[188:191], v[110:113]
	v_mfma_f32_16x16x32_bf16 v[102:105], v[142:145], v[202:205], v[102:105]
	v_mfma_f32_16x16x32_bf16 v[94:97], v[156:159], v[202:205], v[94:97]
	v_mfma_f32_16x16x32_bf16 v[86:89], v[142:145], v[210:213], v[86:89]
	v_mfma_f32_16x16x32_bf16 v[78:81], v[156:159], v[210:213], v[78:81]
	v_mfma_f32_16x16x32_bf16 v[126:129], v[152:155], v[184:187], v[126:129]
	v_mfma_f32_16x16x32_bf16 v[122:125], v[160:163], v[184:187], v[122:125]
	v_mfma_f32_16x16x32_bf16 v[118:121], v[152:155], v[192:195], v[118:121]
	v_mfma_f32_16x16x32_bf16 v[110:113], v[160:163], v[192:195], v[110:113]
	v_mfma_f32_16x16x32_bf16 v[102:105], v[152:155], v[206:209], v[102:105]
	v_mfma_f32_16x16x32_bf16 v[94:97], v[160:163], v[206:209], v[94:97]
	v_mfma_f32_16x16x32_bf16 v[86:89], v[152:155], v[214:217], v[86:89]
	v_mfma_f32_16x16x32_bf16 v[78:81], v[160:163], v[214:217], v[78:81]
	v_mfma_f32_16x16x32_bf16 v[114:117], v[164:167], v[180:183], v[114:117]
	v_mfma_f32_16x16x32_bf16 v[106:109], v[172:175], v[180:183], v[106:109]
	v_mfma_f32_16x16x32_bf16 v[98:101], v[164:167], v[188:191], v[98:101]
	v_mfma_f32_16x16x32_bf16 v[90:93], v[172:175], v[188:191], v[90:93]
	v_mfma_f32_16x16x32_bf16 v[82:85], v[164:167], v[202:205], v[82:85]
	v_mfma_f32_16x16x32_bf16 v[74:77], v[172:175], v[202:205], v[74:77]
	v_mfma_f32_16x16x32_bf16 v[70:73], v[164:167], v[210:213], v[70:73]
	v_mfma_f32_16x16x32_bf16 v[66:69], v[172:175], v[210:213], v[66:69]
	v_mfma_f32_16x16x32_bf16 v[114:117], v[168:171], v[184:187], v[114:117]
	v_mfma_f32_16x16x32_bf16 v[106:109], v[176:179], v[184:187], v[106:109]
	v_mfma_f32_16x16x32_bf16 v[98:101], v[168:171], v[192:195], v[98:101]
	v_mfma_f32_16x16x32_bf16 v[90:93], v[176:179], v[192:195], v[90:93]
	v_mfma_f32_16x16x32_bf16 v[82:85], v[168:171], v[206:209], v[82:85]
	v_mfma_f32_16x16x32_bf16 v[74:77], v[176:179], v[206:209], v[74:77]
	v_mfma_f32_16x16x32_bf16 v[70:73], v[168:171], v[214:217], v[70:73]
	v_mfma_f32_16x16x32_bf16 v[66:69], v[176:179], v[214:217], v[66:69]
	s_barrier
	s_setprio 0
	s_add_i32 s1, s72, s26
	v_lshl_add_u64 v[146:147], s[8:9], 0, v[196:197]
	s_mov_b32 m0, s1
	ds_read_b128 v[180:183], v151 offset:16384
	ds_read_b128 v[184:187], v151 offset:17408
	ds_read_b128 v[188:191], v151 offset:18432
	ds_read_b128 v[192:195], v151 offset:19456
	ds_read_b128 v[202:205], v151 offset:20480
	ds_read_b128 v[206:209], v151 offset:21504
	ds_read_b128 v[210:213], v151 offset:22528
	ds_read_b128 v[214:217], v151 offset:23552
	global_load_lds_dwordx4 v[146:147], off
	s_add_i32 m0, s1, 0x2000
	s_add_u32 s72, s8, 0x80000
	v_lshl_add_u64 v[218:219], s[8:9], 0, v[130:131]
	s_addc_u32 s73, s9, 0
	s_add_i32 s0, s0, s26
	global_load_lds_dwordx4 v[218:219], off
	v_lshl_add_u64 v[220:221], s[72:73], 0, v[196:197]
	s_mov_b32 m0, s0
	v_lshl_add_u64 v[222:223], s[62:63], 0, v[132:133]
	global_load_lds_dwordx4 v[220:221], off
	v_lshl_add_u64 v[220:221], s[72:73], 0, v[130:131]
	s_add_i32 m0, s0, 0x2000
	s_nop 0
	global_load_lds_dwordx4 v[220:221], off
	v_lshl_add_u64 v[220:221], s[62:63], 0, v[134:135]
	s_mov_b32 m0, s27
	s_nop 0
	global_load_lds_dwordx4 v[220:221], off
	s_mov_b32 m0, s28
	s_nop 0
	global_load_lds_dwordx4 v[222:223], off
	s_waitcnt vmcnt(8)
	s_waitcnt lgkmcnt(0)
	s_setprio 1
	s_barrier
	v_mfma_f32_16x16x32_bf16 v[62:65], v[142:145], v[180:183], v[62:65]
	v_mfma_f32_16x16x32_bf16 v[58:61], v[156:159], v[180:183], v[58:61]
	v_mfma_f32_16x16x32_bf16 v[54:57], v[142:145], v[188:191], v[54:57]
	v_mfma_f32_16x16x32_bf16 v[46:49], v[156:159], v[188:191], v[46:49]
	v_mfma_f32_16x16x32_bf16 v[38:41], v[142:145], v[202:205], v[38:41]
	v_mfma_f32_16x16x32_bf16 v[30:33], v[156:159], v[202:205], v[30:33]
	v_mfma_f32_16x16x32_bf16 v[22:25], v[142:145], v[210:213], v[22:25]
	v_mfma_f32_16x16x32_bf16 v[14:17], v[156:159], v[210:213], v[14:17]
	v_mfma_f32_16x16x32_bf16 v[62:65], v[152:155], v[184:187], v[62:65]
	v_mfma_f32_16x16x32_bf16 v[58:61], v[160:163], v[184:187], v[58:61]
	v_mfma_f32_16x16x32_bf16 v[54:57], v[152:155], v[192:195], v[54:57]
	v_mfma_f32_16x16x32_bf16 v[46:49], v[160:163], v[192:195], v[46:49]
	v_mfma_f32_16x16x32_bf16 v[38:41], v[152:155], v[206:209], v[38:41]
	v_mfma_f32_16x16x32_bf16 v[30:33], v[160:163], v[206:209], v[30:33]
	v_mfma_f32_16x16x32_bf16 v[22:25], v[152:155], v[214:217], v[22:25]
	v_mfma_f32_16x16x32_bf16 v[14:17], v[160:163], v[214:217], v[14:17]
	v_mfma_f32_16x16x32_bf16 v[50:53], v[164:167], v[180:183], v[50:53]
	v_mfma_f32_16x16x32_bf16 v[42:45], v[172:175], v[180:183], v[42:45]
	v_mfma_f32_16x16x32_bf16 v[34:37], v[164:167], v[188:191], v[34:37]
	v_mfma_f32_16x16x32_bf16 v[26:29], v[172:175], v[188:191], v[26:29]
	v_mfma_f32_16x16x32_bf16 v[18:21], v[164:167], v[202:205], v[18:21]
	v_mfma_f32_16x16x32_bf16 v[10:13], v[172:175], v[202:205], v[10:13]
	v_mfma_f32_16x16x32_bf16 v[6:9], v[164:167], v[210:213], v[6:9]
	v_mfma_f32_16x16x32_bf16 v[2:5], v[172:175], v[210:213], v[2:5]
	v_mfma_f32_16x16x32_bf16 v[50:53], v[168:171], v[184:187], v[50:53]
	v_mfma_f32_16x16x32_bf16 v[42:45], v[176:179], v[184:187], v[42:45]
	v_mfma_f32_16x16x32_bf16 v[34:37], v[168:171], v[192:195], v[34:37]
	v_mfma_f32_16x16x32_bf16 v[26:29], v[176:179], v[192:195], v[26:29]
	v_mfma_f32_16x16x32_bf16 v[18:21], v[168:171], v[206:209], v[18:21]
	v_mfma_f32_16x16x32_bf16 v[10:13], v[176:179], v[206:209], v[10:13]
	v_mfma_f32_16x16x32_bf16 v[6:9], v[168:171], v[214:217], v[6:9]
	v_mfma_f32_16x16x32_bf16 v[2:5], v[176:179], v[214:217], v[2:5]
	s_barrier
	s_setprio 0
	s_add_i32 s0, 0, 0x18000
	s_add_i32 s1, 0, 0x1c000
	v_add_u32_e32 v160, s0, v149
	v_add_u32_e32 v176, s1, v149
	ds_read_b128 v[142:145], v160
	ds_read_b128 v[152:155], v160 offset:1024
	ds_read_b128 v[156:159], v160 offset:2048
	ds_read_b128 v[160:163], v160 offset:3072
	ds_read_b128 v[164:167], v176
	ds_read_b128 v[168:171], v176 offset:1024
	ds_read_b128 v[172:175], v176 offset:2048
	ds_read_b128 v[176:179], v176 offset:3072
	s_add_u32 s62, s62, 0x80000
	s_addc_u32 s63, s63, 0
	s_mov_b32 m0, s29
	v_lshl_add_u64 v[224:225], s[62:63], 0, v[134:135]
	ds_read_b128 v[180:183], v151 offset:32768
	ds_read_b128 v[184:187], v151 offset:33792
	ds_read_b128 v[188:191], v151 offset:34816
	ds_read_b128 v[192:195], v151 offset:35840
	ds_read_b128 v[202:205], v151 offset:36864
	ds_read_b128 v[206:209], v151 offset:37888
	ds_read_b128 v[210:213], v151 offset:38912
	ds_read_b128 v[214:217], v151 offset:39936
	global_load_lds_dwordx4 v[224:225], off
	v_lshl_add_u64 v[224:225], s[62:63], 0, v[132:133]
	s_mov_b32 m0, s30
	s_nop 0
	global_load_lds_dwordx4 v[224:225], off
	s_waitcnt vmcnt(8)
	s_waitcnt lgkmcnt(0)
	s_setprio 1
	s_barrier
	v_mfma_f32_16x16x32_bf16 v[126:129], v[142:145], v[180:183], v[126:129]
	v_mfma_f32_16x16x32_bf16 v[122:125], v[156:159], v[180:183], v[122:125]
	v_mfma_f32_16x16x32_bf16 v[118:121], v[142:145], v[188:191], v[118:121]
	v_mfma_f32_16x16x32_bf16 v[110:113], v[156:159], v[188:191], v[110:113]
	v_mfma_f32_16x16x32_bf16 v[102:105], v[142:145], v[202:205], v[102:105]
	v_mfma_f32_16x16x32_bf16 v[94:97], v[156:159], v[202:205], v[94:97]
	v_mfma_f32_16x16x32_bf16 v[86:89], v[142:145], v[210:213], v[86:89]
	v_mfma_f32_16x16x32_bf16 v[78:81], v[156:159], v[210:213], v[78:81]
	v_mfma_f32_16x16x32_bf16 v[126:129], v[152:155], v[184:187], v[126:129]
	v_mfma_f32_16x16x32_bf16 v[122:125], v[160:163], v[184:187], v[122:125]
	v_mfma_f32_16x16x32_bf16 v[118:121], v[152:155], v[192:195], v[118:121]
	v_mfma_f32_16x16x32_bf16 v[110:113], v[160:163], v[192:195], v[110:113]
	v_mfma_f32_16x16x32_bf16 v[102:105], v[152:155], v[206:209], v[102:105]
	v_mfma_f32_16x16x32_bf16 v[94:97], v[160:163], v[206:209], v[94:97]
	v_mfma_f32_16x16x32_bf16 v[86:89], v[152:155], v[214:217], v[86:89]
	v_mfma_f32_16x16x32_bf16 v[78:81], v[160:163], v[214:217], v[78:81]
	v_mfma_f32_16x16x32_bf16 v[114:117], v[164:167], v[180:183], v[114:117]
	v_mfma_f32_16x16x32_bf16 v[106:109], v[172:175], v[180:183], v[106:109]
	v_mfma_f32_16x16x32_bf16 v[98:101], v[164:167], v[188:191], v[98:101]
	v_mfma_f32_16x16x32_bf16 v[90:93], v[172:175], v[188:191], v[90:93]
	v_mfma_f32_16x16x32_bf16 v[82:85], v[164:167], v[202:205], v[82:85]
	v_mfma_f32_16x16x32_bf16 v[74:77], v[172:175], v[202:205], v[74:77]
	v_mfma_f32_16x16x32_bf16 v[70:73], v[164:167], v[210:213], v[70:73]
	v_mfma_f32_16x16x32_bf16 v[66:69], v[172:175], v[210:213], v[66:69]
	v_mfma_f32_16x16x32_bf16 v[114:117], v[168:171], v[184:187], v[114:117]
	v_mfma_f32_16x16x32_bf16 v[106:109], v[176:179], v[184:187], v[106:109]
	v_mfma_f32_16x16x32_bf16 v[98:101], v[168:171], v[192:195], v[98:101]
	v_mfma_f32_16x16x32_bf16 v[90:93], v[176:179], v[192:195], v[90:93]
	v_mfma_f32_16x16x32_bf16 v[82:85], v[168:171], v[206:209], v[82:85]
	v_mfma_f32_16x16x32_bf16 v[74:77], v[176:179], v[206:209], v[74:77]
	v_mfma_f32_16x16x32_bf16 v[70:73], v[168:171], v[214:217], v[70:73]
	v_mfma_f32_16x16x32_bf16 v[66:69], v[176:179], v[214:217], v[66:69]
	s_barrier
	s_setprio 0
	s_add_i32 s0, s0, s26
	v_lshl_add_u64 v[146:147], v[146:147], 0, s[16:17]
	s_mov_b32 m0, s0
	ds_read_b128 v[180:183], v151 offset:49152
	ds_read_b128 v[184:187], v151 offset:50176
	ds_read_b128 v[188:191], v151 offset:51200
	ds_read_b128 v[192:195], v151 offset:52224
	ds_read_b128 v[202:205], v151 offset:53248
	ds_read_b128 v[206:209], v151 offset:54272
	ds_read_b128 v[210:213], v151 offset:55296
	ds_read_b128 v[214:217], v151 offset:56320
	global_load_lds_dwordx4 v[146:147], off
	s_add_i32 m0, s0, 0x2000
	s_add_u32 s8, s8, 0x80080
	v_lshl_add_u64 v[146:147], v[218:219], 0, s[16:17]
	s_addc_u32 s9, s9, 0
	s_add_i32 s0, s1, s26
	global_load_lds_dwordx4 v[146:147], off
	v_lshl_add_u64 v[146:147], s[8:9], 0, v[196:197]
	s_mov_b32 m0, s0
	s_nop 0
	global_load_lds_dwordx4 v[146:147], off
	v_lshl_add_u64 v[146:147], s[8:9], 0, v[130:131]
	s_add_i32 m0, s0, 0x2000
	s_nop 0
	global_load_lds_dwordx4 v[146:147], off
	v_lshl_add_u64 v[146:147], v[220:221], 0, s[16:17]
	s_mov_b32 m0, s31
	s_nop 0
	global_load_lds_dwordx4 v[146:147], off
	v_lshl_add_u64 v[146:147], v[222:223], 0, s[16:17]
	s_mov_b32 m0, s34
	s_nop 0
	global_load_lds_dwordx4 v[146:147], off
	s_waitcnt vmcnt(8)
	s_waitcnt lgkmcnt(0)
	s_setprio 1
	s_barrier
	v_mfma_f32_16x16x32_bf16 v[62:65], v[142:145], v[180:183], v[62:65]
	v_mfma_f32_16x16x32_bf16 v[58:61], v[156:159], v[180:183], v[58:61]
	v_mfma_f32_16x16x32_bf16 v[54:57], v[142:145], v[188:191], v[54:57]
	v_mfma_f32_16x16x32_bf16 v[46:49], v[156:159], v[188:191], v[46:49]
	v_mfma_f32_16x16x32_bf16 v[38:41], v[142:145], v[202:205], v[38:41]
	v_mfma_f32_16x16x32_bf16 v[30:33], v[156:159], v[202:205], v[30:33]
	v_mfma_f32_16x16x32_bf16 v[22:25], v[142:145], v[210:213], v[22:25]
	v_mfma_f32_16x16x32_bf16 v[14:17], v[156:159], v[210:213], v[14:17]
	v_mfma_f32_16x16x32_bf16 v[62:65], v[152:155], v[184:187], v[62:65]
	v_mfma_f32_16x16x32_bf16 v[58:61], v[160:163], v[184:187], v[58:61]
	v_mfma_f32_16x16x32_bf16 v[54:57], v[152:155], v[192:195], v[54:57]
	v_mfma_f32_16x16x32_bf16 v[46:49], v[160:163], v[192:195], v[46:49]
	v_mfma_f32_16x16x32_bf16 v[38:41], v[152:155], v[206:209], v[38:41]
	v_mfma_f32_16x16x32_bf16 v[30:33], v[160:163], v[206:209], v[30:33]
	v_mfma_f32_16x16x32_bf16 v[22:25], v[152:155], v[214:217], v[22:25]
	v_mfma_f32_16x16x32_bf16 v[14:17], v[160:163], v[214:217], v[14:17]
	v_mfma_f32_16x16x32_bf16 v[50:53], v[164:167], v[180:183], v[50:53]
	v_mfma_f32_16x16x32_bf16 v[42:45], v[172:175], v[180:183], v[42:45]
	v_mfma_f32_16x16x32_bf16 v[34:37], v[164:167], v[188:191], v[34:37]
	v_mfma_f32_16x16x32_bf16 v[26:29], v[172:175], v[188:191], v[26:29]
	v_mfma_f32_16x16x32_bf16 v[18:21], v[164:167], v[202:205], v[18:21]
	v_mfma_f32_16x16x32_bf16 v[10:13], v[172:175], v[202:205], v[10:13]
	v_mfma_f32_16x16x32_bf16 v[6:9], v[164:167], v[210:213], v[6:9]
	v_mfma_f32_16x16x32_bf16 v[2:5], v[172:175], v[210:213], v[2:5]
	v_mfma_f32_16x16x32_bf16 v[50:53], v[168:171], v[184:187], v[50:53]
	v_mfma_f32_16x16x32_bf16 v[42:45], v[176:179], v[184:187], v[42:45]
	v_mfma_f32_16x16x32_bf16 v[34:37], v[168:171], v[192:195], v[34:37]
	v_mfma_f32_16x16x32_bf16 v[26:29], v[176:179], v[192:195], v[26:29]
	v_mfma_f32_16x16x32_bf16 v[18:21], v[168:171], v[206:209], v[18:21]
	v_mfma_f32_16x16x32_bf16 v[10:13], v[176:179], v[206:209], v[10:13]
	v_mfma_f32_16x16x32_bf16 v[6:9], v[168:171], v[214:217], v[6:9]
	v_mfma_f32_16x16x32_bf16 v[2:5], v[176:179], v[214:217], v[2:5]
	s_barrier
	s_setprio 0
	s_add_u32 s69, s69, 0x100
	s_addc_u32 s70, s70, 0
	s_add_u32 s58, s58, 0x100
	s_addc_u32 s59, s59, 0
	s_cmp_ge_i32 s71, s64
	s_mov_b32 s8, s71
	s_cbranch_scc0 .LBB0_1135
	s_and_b64 vcc, exec, s[38:39]
	s_cbranch_vccz .LBB0_1138
	s_barrier

.LBB0_2239:
	s_add_i32 s73, s8, 2
	s_add_u32 s0, s44, 0xfff00080
	s_addc_u32 s1, s45, -1
	s_add_i32 s77, 0, 0x10000
	s_cmp_eq_u32 s70, s8
	s_cselect_b32 s67, s51, s1
	s_cselect_b32 s66, s53, s0
	s_cselect_b32 s9, s49, s72
	s_cselect_b32 s8, s69, s71
	s_add_i32 s78, 0, 0x14000
	v_add_u32_e32 v142, s77, v244
	v_add_u32_e32 v158, s78, v244
	ds_read_b128 v[130:133], v142
	ds_read_b128 v[134:137], v142 offset:1024
	ds_read_b128 v[138:141], v142 offset:2048
	ds_read_b128 v[142:145], v142 offset:3072
	ds_read_b128 v[146:149], v158
	ds_read_b128 v[150:153], v158 offset:1024
	ds_read_b128 v[154:157], v158 offset:2048
	ds_read_b128 v[158:161], v158 offset:3072
	v_lshl_add_u64 v[194:195], s[44:45], 0, v[210:211]
	s_add_i32 m0, s3, 0xc000
	ds_read_b128 v[162:165], v246
	ds_read_b128 v[166:169], v246 offset:1024
	ds_read_b128 v[170:173], v246 offset:2048
	ds_read_b128 v[174:177], v246 offset:3072
	ds_read_b128 v[178:181], v246 offset:4096
	ds_read_b128 v[182:185], v246 offset:5120
	ds_read_b128 v[186:189], v246 offset:6144
	ds_read_b128 v[190:193], v246 offset:7168
	global_load_lds_dwordx4 v[194:195], off
	v_lshl_add_u64 v[194:195], s[44:45], 0, v[208:209]
	s_add_i32 m0, s3, 0xe000
	s_nop 0
	global_load_lds_dwordx4 v[194:195], off
	s_waitcnt vmcnt(8)
	s_waitcnt lgkmcnt(0)
	s_setprio 1
	s_barrier
	v_mfma_f32_16x16x32_bf16 v[126:129], v[130:133], v[162:165], v[126:129]
	v_mfma_f32_16x16x32_bf16 v[122:125], v[138:141], v[162:165], v[122:125]
	v_mfma_f32_16x16x32_bf16 v[110:113], v[130:133], v[170:173], v[110:113]
	v_mfma_f32_16x16x32_bf16 v[106:109], v[138:141], v[170:173], v[106:109]
	v_mfma_f32_16x16x32_bf16 v[94:97], v[130:133], v[178:181], v[94:97]
	v_mfma_f32_16x16x32_bf16 v[90:93], v[138:141], v[178:181], v[90:93]
	v_mfma_f32_16x16x32_bf16 v[78:81], v[130:133], v[186:189], v[78:81]
	v_mfma_f32_16x16x32_bf16 v[74:77], v[138:141], v[186:189], v[74:77]
	v_mfma_f32_16x16x32_bf16 v[126:129], v[134:137], v[166:169], v[126:129]
	v_mfma_f32_16x16x32_bf16 v[122:125], v[142:145], v[166:169], v[122:125]
	v_mfma_f32_16x16x32_bf16 v[110:113], v[134:137], v[174:177], v[110:113]
	v_mfma_f32_16x16x32_bf16 v[106:109], v[142:145], v[174:177], v[106:109]
	v_mfma_f32_16x16x32_bf16 v[94:97], v[134:137], v[182:185], v[94:97]
	v_mfma_f32_16x16x32_bf16 v[90:93], v[142:145], v[182:185], v[90:93]
	v_mfma_f32_16x16x32_bf16 v[78:81], v[134:137], v[190:193], v[78:81]
	v_mfma_f32_16x16x32_bf16 v[74:77], v[142:145], v[190:193], v[74:77]
	v_mfma_f32_16x16x32_bf16 v[118:121], v[146:149], v[162:165], v[118:121]
	v_mfma_f32_16x16x32_bf16 v[114:117], v[154:157], v[162:165], v[114:117]
	v_mfma_f32_16x16x32_bf16 v[102:105], v[146:149], v[170:173], v[102:105]
	v_mfma_f32_16x16x32_bf16 v[98:101], v[154:157], v[170:173], v[98:101]
	v_mfma_f32_16x16x32_bf16 v[86:89], v[146:149], v[178:181], v[86:89]
	v_mfma_f32_16x16x32_bf16 v[82:85], v[154:157], v[178:181], v[82:85]
	v_mfma_f32_16x16x32_bf16 v[70:73], v[146:149], v[186:189], v[70:73]
	v_mfma_f32_16x16x32_bf16 v[66:69], v[154:157], v[186:189], v[66:69]
	v_mfma_f32_16x16x32_bf16 v[118:121], v[150:153], v[166:169], v[118:121]
	v_mfma_f32_16x16x32_bf16 v[114:117], v[158:161], v[166:169], v[114:117]
	v_mfma_f32_16x16x32_bf16 v[102:105], v[150:153], v[174:177], v[102:105]
	v_mfma_f32_16x16x32_bf16 v[98:101], v[158:161], v[174:177], v[98:101]
	v_mfma_f32_16x16x32_bf16 v[86:89], v[150:153], v[182:185], v[86:89]
	v_mfma_f32_16x16x32_bf16 v[82:85], v[158:161], v[182:185], v[82:85]
	v_mfma_f32_16x16x32_bf16 v[70:73], v[150:153], v[190:193], v[70:73]
	v_mfma_f32_16x16x32_bf16 v[66:69], v[158:161], v[190:193], v[66:69]
	s_barrier
	s_setprio 0
	s_add_i32 s0, s77, s2
	v_lshl_add_u64 v[194:195], s[8:9], 0, v[196:197]
	s_mov_b32 m0, s0
	ds_read_b128 v[162:165], v246 offset:16384
	ds_read_b128 v[166:169], v246 offset:17408
	ds_read_b128 v[170:173], v246 offset:18432
	ds_read_b128 v[174:177], v246 offset:19456
	ds_read_b128 v[178:181], v246 offset:20480
	ds_read_b128 v[182:185], v246 offset:21504
	ds_read_b128 v[186:189], v246 offset:22528
	ds_read_b128 v[190:193], v246 offset:23552
	global_load_lds_dwordx4 v[194:195], off
	s_add_i32 m0, s0, 0x2000
	s_add_u32 s0, s8, 0x100000
	v_lshl_add_u64 v[212:213], s[8:9], 0, v[202:203]
	s_addc_u32 s1, s9, 0
	s_add_i32 s77, s78, s2
	global_load_lds_dwordx4 v[212:213], off
	v_lshl_add_u64 v[214:215], s[0:1], 0, v[196:197]
	s_mov_b32 m0, s77
	v_lshl_add_u64 v[216:217], s[66:67], 0, v[204:205]
	global_load_lds_dwordx4 v[214:215], off
	v_lshl_add_u64 v[214:215], s[0:1], 0, v[202:203]
	s_add_i32 m0, s77, 0x2000
	s_nop 0
	global_load_lds_dwordx4 v[214:215], off
	v_lshl_add_u64 v[214:215], s[66:67], 0, v[206:207]
	s_mov_b32 m0, s3
	s_nop 0
	global_load_lds_dwordx4 v[214:215], off
	s_mov_b32 m0, s10
	s_nop 0
	global_load_lds_dwordx4 v[216:217], off
	s_waitcnt vmcnt(8)
	s_waitcnt lgkmcnt(0)
	s_setprio 1
	s_barrier
	v_mfma_f32_16x16x32_bf16 v[62:65], v[130:133], v[162:165], v[62:65]
	v_mfma_f32_16x16x32_bf16 v[58:61], v[138:141], v[162:165], v[58:61]
	v_mfma_f32_16x16x32_bf16 v[46:49], v[130:133], v[170:173], v[46:49]
	v_mfma_f32_16x16x32_bf16 v[42:45], v[138:141], v[170:173], v[42:45]
	v_mfma_f32_16x16x32_bf16 v[30:33], v[130:133], v[178:181], v[30:33]
	v_mfma_f32_16x16x32_bf16 v[26:29], v[138:141], v[178:181], v[26:29]
	v_mfma_f32_16x16x32_bf16 v[14:17], v[130:133], v[186:189], v[14:17]
	v_mfma_f32_16x16x32_bf16 v[10:13], v[138:141], v[186:189], v[10:13]
	v_mfma_f32_16x16x32_bf16 v[62:65], v[134:137], v[166:169], v[62:65]
	v_mfma_f32_16x16x32_bf16 v[58:61], v[142:145], v[166:169], v[58:61]
	v_mfma_f32_16x16x32_bf16 v[46:49], v[134:137], v[174:177], v[46:49]
	v_mfma_f32_16x16x32_bf16 v[42:45], v[142:145], v[174:177], v[42:45]
	v_mfma_f32_16x16x32_bf16 v[30:33], v[134:137], v[182:185], v[30:33]
	v_mfma_f32_16x16x32_bf16 v[26:29], v[142:145], v[182:185], v[26:29]
	v_mfma_f32_16x16x32_bf16 v[14:17], v[134:137], v[190:193], v[14:17]
	v_mfma_f32_16x16x32_bf16 v[10:13], v[142:145], v[190:193], v[10:13]
	v_mfma_f32_16x16x32_bf16 v[54:57], v[146:149], v[162:165], v[54:57]
	v_mfma_f32_16x16x32_bf16 v[50:53], v[154:157], v[162:165], v[50:53]
	v_mfma_f32_16x16x32_bf16 v[38:41], v[146:149], v[170:173], v[38:41]
	v_mfma_f32_16x16x32_bf16 v[34:37], v[154:157], v[170:173], v[34:37]
	v_mfma_f32_16x16x32_bf16 v[22:25], v[146:149], v[178:181], v[22:25]
	v_mfma_f32_16x16x32_bf16 v[18:21], v[154:157], v[178:181], v[18:21]
	v_mfma_f32_16x16x32_bf16 v[6:9], v[146:149], v[186:189], v[6:9]
	v_mfma_f32_16x16x32_bf16 v[2:5], v[154:157], v[186:189], v[2:5]
	v_mfma_f32_16x16x32_bf16 v[54:57], v[150:153], v[166:169], v[54:57]
	v_mfma_f32_16x16x32_bf16 v[50:53], v[158:161], v[166:169], v[50:53]
	v_mfma_f32_16x16x32_bf16 v[38:41], v[150:153], v[174:177], v[38:41]
	v_mfma_f32_16x16x32_bf16 v[34:37], v[158:161], v[174:177], v[34:37]
	v_mfma_f32_16x16x32_bf16 v[22:25], v[150:153], v[182:185], v[22:25]
	v_mfma_f32_16x16x32_bf16 v[18:21], v[158:161], v[182:185], v[18:21]
	v_mfma_f32_16x16x32_bf16 v[6:9], v[150:153], v[190:193], v[6:9]
	v_mfma_f32_16x16x32_bf16 v[2:5], v[158:161], v[190:193], v[2:5]
	s_barrier
	s_setprio 0
	s_add_i32 s77, 0, 0x18000
	s_add_i32 s78, 0, 0x1c000
	v_add_u32_e32 v142, s77, v244
	v_add_u32_e32 v158, s78, v244
	ds_read_b128 v[130:133], v142
	ds_read_b128 v[134:137], v142 offset:1024
	ds_read_b128 v[138:141], v142 offset:2048
	ds_read_b128 v[142:145], v142 offset:3072
	ds_read_b128 v[146:149], v158
	ds_read_b128 v[150:153], v158 offset:1024
	ds_read_b128 v[154:157], v158 offset:2048
	ds_read_b128 v[158:161], v158 offset:3072
	s_add_u32 s0, s66, 0x100000
	s_addc_u32 s1, s67, 0
	s_mov_b32 m0, s11
	v_lshl_add_u64 v[218:219], s[0:1], 0, v[206:207]
	ds_read_b128 v[162:165], v246 offset:32768
	ds_read_b128 v[166:169], v246 offset:33792
	ds_read_b128 v[170:173], v246 offset:34816
	ds_read_b128 v[174:177], v246 offset:35840
	ds_read_b128 v[178:181], v246 offset:36864
	ds_read_b128 v[182:185], v246 offset:37888
	ds_read_b128 v[186:189], v246 offset:38912
	ds_read_b128 v[190:193], v246 offset:39936
	global_load_lds_dwordx4 v[218:219], off
	v_lshl_add_u64 v[218:219], s[0:1], 0, v[204:205]
	s_mov_b32 m0, s26
	s_nop 0
	global_load_lds_dwordx4 v[218:219], off
	s_waitcnt vmcnt(8)
	s_waitcnt lgkmcnt(0)
	s_setprio 1
	s_barrier
	v_mfma_f32_16x16x32_bf16 v[126:129], v[130:133], v[162:165], v[126:129]
	v_mfma_f32_16x16x32_bf16 v[122:125], v[138:141], v[162:165], v[122:125]
	v_mfma_f32_16x16x32_bf16 v[110:113], v[130:133], v[170:173], v[110:113]
	v_mfma_f32_16x16x32_bf16 v[106:109], v[138:141], v[170:173], v[106:109]
	v_mfma_f32_16x16x32_bf16 v[94:97], v[130:133], v[178:181], v[94:97]
	v_mfma_f32_16x16x32_bf16 v[90:93], v[138:141], v[178:181], v[90:93]
	v_mfma_f32_16x16x32_bf16 v[78:81], v[130:133], v[186:189], v[78:81]
	v_mfma_f32_16x16x32_bf16 v[74:77], v[138:141], v[186:189], v[74:77]
	v_mfma_f32_16x16x32_bf16 v[126:129], v[134:137], v[166:169], v[126:129]
	v_mfma_f32_16x16x32_bf16 v[122:125], v[142:145], v[166:169], v[122:125]
	v_mfma_f32_16x16x32_bf16 v[110:113], v[134:137], v[174:177], v[110:113]
	v_mfma_f32_16x16x32_bf16 v[106:109], v[142:145], v[174:177], v[106:109]
	v_mfma_f32_16x16x32_bf16 v[94:97], v[134:137], v[182:185], v[94:97]
	v_mfma_f32_16x16x32_bf16 v[90:93], v[142:145], v[182:185], v[90:93]
	v_mfma_f32_16x16x32_bf16 v[78:81], v[134:137], v[190:193], v[78:81]
	v_mfma_f32_16x16x32_bf16 v[74:77], v[142:145], v[190:193], v[74:77]
	v_mfma_f32_16x16x32_bf16 v[118:121], v[146:149], v[162:165], v[118:121]
	v_mfma_f32_16x16x32_bf16 v[114:117], v[154:157], v[162:165], v[114:117]
	v_mfma_f32_16x16x32_bf16 v[102:105], v[146:149], v[170:173], v[102:105]
	v_mfma_f32_16x16x32_bf16 v[98:101], v[154:157], v[170:173], v[98:101]
	v_mfma_f32_16x16x32_bf16 v[86:89], v[146:149], v[178:181], v[86:89]
	v_mfma_f32_16x16x32_bf16 v[82:85], v[154:157], v[178:181], v[82:85]
	v_mfma_f32_16x16x32_bf16 v[70:73], v[146:149], v[186:189], v[70:73]
	v_mfma_f32_16x16x32_bf16 v[66:69], v[154:157], v[186:189], v[66:69]
	v_mfma_f32_16x16x32_bf16 v[118:121], v[150:153], v[166:169], v[118:121]
	v_mfma_f32_16x16x32_bf16 v[114:117], v[158:161], v[166:169], v[114:117]
	v_mfma_f32_16x16x32_bf16 v[102:105], v[150:153], v[174:177], v[102:105]
	v_mfma_f32_16x16x32_bf16 v[98:101], v[158:161], v[174:177], v[98:101]
	v_mfma_f32_16x16x32_bf16 v[86:89], v[150:153], v[182:185], v[86:89]
	v_mfma_f32_16x16x32_bf16 v[82:85], v[158:161], v[182:185], v[82:85]
	v_mfma_f32_16x16x32_bf16 v[70:73], v[150:153], v[190:193], v[70:73]
	v_mfma_f32_16x16x32_bf16 v[66:69], v[158:161], v[190:193], v[66:69]
	s_barrier
	s_setprio 0
	s_add_i32 s0, s77, s2
	v_lshl_add_u64 v[194:195], v[194:195], 0, s[16:17]
	s_mov_b32 m0, s0
	ds_read_b128 v[162:165], v246 offset:49152
	ds_read_b128 v[166:169], v246 offset:50176
	ds_read_b128 v[170:173], v246 offset:51200
	ds_read_b128 v[174:177], v246 offset:52224
	ds_read_b128 v[178:181], v246 offset:53248
	ds_read_b128 v[182:185], v246 offset:54272
	ds_read_b128 v[186:189], v246 offset:55296
	ds_read_b128 v[190:193], v246 offset:56320
	global_load_lds_dwordx4 v[194:195], off
	s_add_i32 m0, s0, 0x2000
	s_add_u32 s0, s8, 0x100080
	v_lshl_add_u64 v[194:195], v[212:213], 0, s[16:17]
	s_addc_u32 s1, s9, 0
	s_add_i32 s8, s78, s2
	global_load_lds_dwordx4 v[194:195], off
	v_lshl_add_u64 v[194:195], s[0:1], 0, v[196:197]
	s_mov_b32 m0, s8
	s_nop 0
	global_load_lds_dwordx4 v[194:195], off
	v_lshl_add_u64 v[194:195], s[0:1], 0, v[202:203]
	s_add_i32 m0, s8, 0x2000
	s_nop 0
	global_load_lds_dwordx4 v[194:195], off
	v_lshl_add_u64 v[194:195], v[214:215], 0, s[16:17]
	s_mov_b32 m0, s27
	s_nop 0
	global_load_lds_dwordx4 v[194:195], off
	v_lshl_add_u64 v[194:195], v[216:217], 0, s[16:17]
	s_mov_b32 m0, s28
	s_nop 0
	global_load_lds_dwordx4 v[194:195], off
	s_waitcnt vmcnt(8)
	s_waitcnt lgkmcnt(0)
	s_setprio 1
	s_barrier
	v_mfma_f32_16x16x32_bf16 v[62:65], v[130:133], v[162:165], v[62:65]
	v_mfma_f32_16x16x32_bf16 v[58:61], v[138:141], v[162:165], v[58:61]
	v_mfma_f32_16x16x32_bf16 v[46:49], v[130:133], v[170:173], v[46:49]
	v_mfma_f32_16x16x32_bf16 v[42:45], v[138:141], v[170:173], v[42:45]
	v_mfma_f32_16x16x32_bf16 v[30:33], v[130:133], v[178:181], v[30:33]
	v_mfma_f32_16x16x32_bf16 v[26:29], v[138:141], v[178:181], v[26:29]
	v_mfma_f32_16x16x32_bf16 v[14:17], v[130:133], v[186:189], v[14:17]
	v_mfma_f32_16x16x32_bf16 v[10:13], v[138:141], v[186:189], v[10:13]
	v_mfma_f32_16x16x32_bf16 v[62:65], v[134:137], v[166:169], v[62:65]
	v_mfma_f32_16x16x32_bf16 v[58:61], v[142:145], v[166:169], v[58:61]
	v_mfma_f32_16x16x32_bf16 v[46:49], v[134:137], v[174:177], v[46:49]
	v_mfma_f32_16x16x32_bf16 v[42:45], v[142:145], v[174:177], v[42:45]
	v_mfma_f32_16x16x32_bf16 v[30:33], v[134:137], v[182:185], v[30:33]
	v_mfma_f32_16x16x32_bf16 v[26:29], v[142:145], v[182:185], v[26:29]
	v_mfma_f32_16x16x32_bf16 v[14:17], v[134:137], v[190:193], v[14:17]
	v_mfma_f32_16x16x32_bf16 v[10:13], v[142:145], v[190:193], v[10:13]
	v_mfma_f32_16x16x32_bf16 v[54:57], v[146:149], v[162:165], v[54:57]
	v_mfma_f32_16x16x32_bf16 v[50:53], v[154:157], v[162:165], v[50:53]
	v_mfma_f32_16x16x32_bf16 v[38:41], v[146:149], v[170:173], v[38:41]
	v_mfma_f32_16x16x32_bf16 v[34:37], v[154:157], v[170:173], v[34:37]
	v_mfma_f32_16x16x32_bf16 v[22:25], v[146:149], v[178:181], v[22:25]
	v_mfma_f32_16x16x32_bf16 v[18:21], v[154:157], v[178:181], v[18:21]
	v_mfma_f32_16x16x32_bf16 v[6:9], v[146:149], v[186:189], v[6:9]
	v_mfma_f32_16x16x32_bf16 v[2:5], v[154:157], v[186:189], v[2:5]
	v_mfma_f32_16x16x32_bf16 v[54:57], v[150:153], v[166:169], v[54:57]
	v_mfma_f32_16x16x32_bf16 v[50:53], v[158:161], v[166:169], v[50:53]
	v_mfma_f32_16x16x32_bf16 v[38:41], v[150:153], v[174:177], v[38:41]
	v_mfma_f32_16x16x32_bf16 v[34:37], v[158:161], v[174:177], v[34:37]
	v_mfma_f32_16x16x32_bf16 v[22:25], v[150:153], v[182:185], v[22:25]
	v_mfma_f32_16x16x32_bf16 v[18:21], v[158:161], v[182:185], v[18:21]
	v_mfma_f32_16x16x32_bf16 v[6:9], v[150:153], v[190:193], v[6:9]
	v_mfma_f32_16x16x32_bf16 v[2:5], v[158:161], v[190:193], v[2:5]
	s_barrier
	s_setprio 0
	s_add_u32 s71, s71, 0x100
	s_addc_u32 s72, s72, 0
	s_add_u32 s44, s44, 0x100
	s_addc_u32 s45, s45, 0
	s_cmp_ge_i32 s73, s35
	s_mov_b32 s8, s73
	s_cbranch_scc0 .LBB0_2239
	s_and_b64 vcc, exec, s[46:47]
	s_cbranch_vccz .LBB0_2242
	s_barrier

.LBB0_2357:
	s_add_i32 s77, s8, 2
	s_add_u32 s0, s62, 0xfff80080
	s_addc_u32 s1, s63, -1
	s_add_i32 s78, 0, 0x10000
	s_cmp_eq_u32 s71, s8
	s_cselect_b32 s65, s41, s1
	s_cselect_b32 s64, s45, s0
	s_cselect_b32 s9, s43, s73
	s_cselect_b32 s8, s70, s72
	s_add_i32 s79, 0, 0x14000
	v_add_u32_e32 v142, s78, v188
	v_add_u32_e32 v158, s79, v188
	ds_read_b128 v[130:133], v142
	ds_read_b128 v[134:137], v142 offset:1024
	ds_read_b128 v[138:141], v142 offset:2048
	ds_read_b128 v[142:145], v142 offset:3072
	ds_read_b128 v[146:149], v158
	ds_read_b128 v[150:153], v158 offset:1024
	ds_read_b128 v[154:157], v158 offset:2048
	ds_read_b128 v[158:161], v158 offset:3072
	v_lshl_add_u64 v[194:195], s[62:63], 0, v[178:179]
	s_add_i32 m0, s27, 0xc000
	ds_read_b128 v[162:165], v189
	ds_read_b128 v[180:183], v189 offset:1024
	ds_read_b128 v[184:187], v189 offset:2048
	ds_read_b128 v[190:193], v189 offset:3072
	ds_read_b128 v[202:205], v189 offset:4096
	ds_read_b128 v[206:209], v189 offset:5120
	ds_read_b128 v[210:213], v189 offset:6144
	ds_read_b128 v[214:217], v189 offset:7168
	global_load_lds_dwordx4 v[194:195], off
	v_lshl_add_u64 v[194:195], s[62:63], 0, v[176:177]
	s_add_i32 m0, s27, 0xe000
	s_nop 0
	global_load_lds_dwordx4 v[194:195], off
	s_waitcnt vmcnt(8)
	s_waitcnt lgkmcnt(0)
	s_setprio 1
	s_barrier
	v_mfma_f32_16x16x32_bf16 v[126:129], v[130:133], v[162:165], v[126:129]
	v_mfma_f32_16x16x32_bf16 v[122:125], v[138:141], v[162:165], v[122:125]
	v_mfma_f32_16x16x32_bf16 v[110:113], v[130:133], v[184:187], v[110:113]
	v_mfma_f32_16x16x32_bf16 v[106:109], v[138:141], v[184:187], v[106:109]
	v_mfma_f32_16x16x32_bf16 v[98:101], v[130:133], v[202:205], v[98:101]
	v_mfma_f32_16x16x32_bf16 v[90:93], v[138:141], v[202:205], v[90:93]
	v_mfma_f32_16x16x32_bf16 v[82:85], v[130:133], v[210:213], v[82:85]
	v_mfma_f32_16x16x32_bf16 v[74:77], v[138:141], v[210:213], v[74:77]
	v_mfma_f32_16x16x32_bf16 v[126:129], v[134:137], v[180:183], v[126:129]
	v_mfma_f32_16x16x32_bf16 v[122:125], v[142:145], v[180:183], v[122:125]
	v_mfma_f32_16x16x32_bf16 v[110:113], v[134:137], v[190:193], v[110:113]
	v_mfma_f32_16x16x32_bf16 v[106:109], v[142:145], v[190:193], v[106:109]
	v_mfma_f32_16x16x32_bf16 v[98:101], v[134:137], v[206:209], v[98:101]
	v_mfma_f32_16x16x32_bf16 v[90:93], v[142:145], v[206:209], v[90:93]
	v_mfma_f32_16x16x32_bf16 v[82:85], v[134:137], v[214:217], v[82:85]
	v_mfma_f32_16x16x32_bf16 v[74:77], v[142:145], v[214:217], v[74:77]
	v_mfma_f32_16x16x32_bf16 v[118:121], v[146:149], v[162:165], v[118:121]
	v_mfma_f32_16x16x32_bf16 v[114:117], v[154:157], v[162:165], v[114:117]
	v_mfma_f32_16x16x32_bf16 v[102:105], v[146:149], v[184:187], v[102:105]
	v_mfma_f32_16x16x32_bf16 v[94:97], v[154:157], v[184:187], v[94:97]
	v_mfma_f32_16x16x32_bf16 v[86:89], v[146:149], v[202:205], v[86:89]
	v_mfma_f32_16x16x32_bf16 v[78:81], v[154:157], v[202:205], v[78:81]
	v_mfma_f32_16x16x32_bf16 v[70:73], v[146:149], v[210:213], v[70:73]
	v_mfma_f32_16x16x32_bf16 v[66:69], v[154:157], v[210:213], v[66:69]
	v_mfma_f32_16x16x32_bf16 v[118:121], v[150:153], v[180:183], v[118:121]
	v_mfma_f32_16x16x32_bf16 v[114:117], v[158:161], v[180:183], v[114:117]
	v_mfma_f32_16x16x32_bf16 v[102:105], v[150:153], v[190:193], v[102:105]
	v_mfma_f32_16x16x32_bf16 v[94:97], v[158:161], v[190:193], v[94:97]
	v_mfma_f32_16x16x32_bf16 v[86:89], v[150:153], v[206:209], v[86:89]
	v_mfma_f32_16x16x32_bf16 v[78:81], v[158:161], v[206:209], v[78:81]
	v_mfma_f32_16x16x32_bf16 v[70:73], v[150:153], v[214:217], v[70:73]
	v_mfma_f32_16x16x32_bf16 v[66:69], v[158:161], v[214:217], v[66:69]
	s_barrier
	s_setprio 0
	s_add_i32 s0, s78, s26
	v_lshl_add_u64 v[194:195], s[8:9], 0, v[196:197]
	s_mov_b32 m0, s0
	ds_read_b128 v[162:165], v189 offset:16384
	ds_read_b128 v[180:183], v189 offset:17408
	ds_read_b128 v[184:187], v189 offset:18432
	ds_read_b128 v[190:193], v189 offset:19456
	ds_read_b128 v[202:205], v189 offset:20480
	ds_read_b128 v[206:209], v189 offset:21504
	ds_read_b128 v[210:213], v189 offset:22528
	ds_read_b128 v[214:217], v189 offset:23552
	global_load_lds_dwordx4 v[194:195], off
	s_add_i32 m0, s0, 0x2000
	s_add_u32 s0, s8, 0x80000
	v_lshl_add_u64 v[218:219], s[8:9], 0, v[170:171]
	s_addc_u32 s1, s9, 0
	s_add_i32 s78, s79, s26
	global_load_lds_dwordx4 v[218:219], off
	v_lshl_add_u64 v[220:221], s[0:1], 0, v[196:197]
	s_mov_b32 m0, s78
	v_lshl_add_u64 v[222:223], s[64:65], 0, v[168:169]
	global_load_lds_dwordx4 v[220:221], off
	v_lshl_add_u64 v[220:221], s[0:1], 0, v[170:171]
	s_add_i32 m0, s78, 0x2000
	s_nop 0
	global_load_lds_dwordx4 v[220:221], off
	v_lshl_add_u64 v[220:221], s[64:65], 0, v[166:167]
	s_mov_b32 m0, s27
	s_nop 0
	global_load_lds_dwordx4 v[220:221], off
	s_mov_b32 m0, s28
	s_nop 0
	global_load_lds_dwordx4 v[222:223], off
	s_waitcnt vmcnt(8)
	s_waitcnt lgkmcnt(0)
	s_setprio 1
	s_barrier
	v_mfma_f32_16x16x32_bf16 v[62:65], v[130:133], v[162:165], v[62:65]
	v_mfma_f32_16x16x32_bf16 v[58:61], v[138:141], v[162:165], v[58:61]
	v_mfma_f32_16x16x32_bf16 v[50:53], v[130:133], v[184:187], v[50:53]
	v_mfma_f32_16x16x32_bf16 v[42:45], v[138:141], v[184:187], v[42:45]
	v_mfma_f32_16x16x32_bf16 v[34:37], v[130:133], v[202:205], v[34:37]
	v_mfma_f32_16x16x32_bf16 v[26:29], v[138:141], v[202:205], v[26:29]
	v_mfma_f32_16x16x32_bf16 v[18:21], v[130:133], v[210:213], v[18:21]
	v_mfma_f32_16x16x32_bf16 v[10:13], v[138:141], v[210:213], v[10:13]
	v_mfma_f32_16x16x32_bf16 v[62:65], v[134:137], v[180:183], v[62:65]
	v_mfma_f32_16x16x32_bf16 v[58:61], v[142:145], v[180:183], v[58:61]
	v_mfma_f32_16x16x32_bf16 v[50:53], v[134:137], v[190:193], v[50:53]
	v_mfma_f32_16x16x32_bf16 v[42:45], v[142:145], v[190:193], v[42:45]
	v_mfma_f32_16x16x32_bf16 v[34:37], v[134:137], v[206:209], v[34:37]
	v_mfma_f32_16x16x32_bf16 v[26:29], v[142:145], v[206:209], v[26:29]
	v_mfma_f32_16x16x32_bf16 v[18:21], v[134:137], v[214:217], v[18:21]
	v_mfma_f32_16x16x32_bf16 v[10:13], v[142:145], v[214:217], v[10:13]
	v_mfma_f32_16x16x32_bf16 v[54:57], v[146:149], v[162:165], v[54:57]
	v_mfma_f32_16x16x32_bf16 v[46:49], v[154:157], v[162:165], v[46:49]
	v_mfma_f32_16x16x32_bf16 v[38:41], v[146:149], v[184:187], v[38:41]
	v_mfma_f32_16x16x32_bf16 v[30:33], v[154:157], v[184:187], v[30:33]
	v_mfma_f32_16x16x32_bf16 v[22:25], v[146:149], v[202:205], v[22:25]
	v_mfma_f32_16x16x32_bf16 v[14:17], v[154:157], v[202:205], v[14:17]
	v_mfma_f32_16x16x32_bf16 v[6:9], v[146:149], v[210:213], v[6:9]
	v_mfma_f32_16x16x32_bf16 v[2:5], v[154:157], v[210:213], v[2:5]
	v_mfma_f32_16x16x32_bf16 v[54:57], v[150:153], v[180:183], v[54:57]
	v_mfma_f32_16x16x32_bf16 v[46:49], v[158:161], v[180:183], v[46:49]
	v_mfma_f32_16x16x32_bf16 v[38:41], v[150:153], v[190:193], v[38:41]
	v_mfma_f32_16x16x32_bf16 v[30:33], v[158:161], v[190:193], v[30:33]
	v_mfma_f32_16x16x32_bf16 v[22:25], v[150:153], v[206:209], v[22:25]
	v_mfma_f32_16x16x32_bf16 v[14:17], v[158:161], v[206:209], v[14:17]
	v_mfma_f32_16x16x32_bf16 v[6:9], v[150:153], v[214:217], v[6:9]
	v_mfma_f32_16x16x32_bf16 v[2:5], v[158:161], v[214:217], v[2:5]
	s_barrier
	s_setprio 0
	s_add_i32 s78, 0, 0x18000
	s_add_i32 s79, 0, 0x1c000
	v_add_u32_e32 v142, s78, v188
	v_add_u32_e32 v158, s79, v188
	ds_read_b128 v[130:133], v142
	ds_read_b128 v[134:137], v142 offset:1024
	ds_read_b128 v[138:141], v142 offset:2048
	ds_read_b128 v[142:145], v142 offset:3072
	ds_read_b128 v[146:149], v158
	ds_read_b128 v[150:153], v158 offset:1024
	ds_read_b128 v[154:157], v158 offset:2048
	ds_read_b128 v[158:161], v158 offset:3072
	s_add_u32 s0, s64, 0x80000
	s_addc_u32 s1, s65, 0
	s_mov_b32 m0, s29
	v_lshl_add_u64 v[224:225], s[0:1], 0, v[166:167]
	ds_read_b128 v[162:165], v189 offset:32768
	ds_read_b128 v[180:183], v189 offset:33792
	ds_read_b128 v[184:187], v189 offset:34816
	ds_read_b128 v[190:193], v189 offset:35840
	ds_read_b128 v[202:205], v189 offset:36864
	ds_read_b128 v[206:209], v189 offset:37888
	ds_read_b128 v[210:213], v189 offset:38912
	ds_read_b128 v[214:217], v189 offset:39936
	global_load_lds_dwordx4 v[224:225], off
	v_lshl_add_u64 v[224:225], s[0:1], 0, v[168:169]
	s_mov_b32 m0, s30
	s_nop 0
	global_load_lds_dwordx4 v[224:225], off
	s_waitcnt vmcnt(8)
	s_waitcnt lgkmcnt(0)
	s_setprio 1
	s_barrier
	v_mfma_f32_16x16x32_bf16 v[126:129], v[130:133], v[162:165], v[126:129]
	v_mfma_f32_16x16x32_bf16 v[122:125], v[138:141], v[162:165], v[122:125]
	v_mfma_f32_16x16x32_bf16 v[110:113], v[130:133], v[184:187], v[110:113]
	v_mfma_f32_16x16x32_bf16 v[106:109], v[138:141], v[184:187], v[106:109]
	v_mfma_f32_16x16x32_bf16 v[98:101], v[130:133], v[202:205], v[98:101]
	v_mfma_f32_16x16x32_bf16 v[90:93], v[138:141], v[202:205], v[90:93]
	v_mfma_f32_16x16x32_bf16 v[82:85], v[130:133], v[210:213], v[82:85]
	v_mfma_f32_16x16x32_bf16 v[74:77], v[138:141], v[210:213], v[74:77]
	v_mfma_f32_16x16x32_bf16 v[126:129], v[134:137], v[180:183], v[126:129]
	v_mfma_f32_16x16x32_bf16 v[122:125], v[142:145], v[180:183], v[122:125]
	v_mfma_f32_16x16x32_bf16 v[110:113], v[134:137], v[190:193], v[110:113]
	v_mfma_f32_16x16x32_bf16 v[106:109], v[142:145], v[190:193], v[106:109]
	v_mfma_f32_16x16x32_bf16 v[98:101], v[134:137], v[206:209], v[98:101]
	v_mfma_f32_16x16x32_bf16 v[90:93], v[142:145], v[206:209], v[90:93]
	v_mfma_f32_16x16x32_bf16 v[82:85], v[134:137], v[214:217], v[82:85]
	v_mfma_f32_16x16x32_bf16 v[74:77], v[142:145], v[214:217], v[74:77]
	v_mfma_f32_16x16x32_bf16 v[118:121], v[146:149], v[162:165], v[118:121]
	v_mfma_f32_16x16x32_bf16 v[114:117], v[154:157], v[162:165], v[114:117]
	v_mfma_f32_16x16x32_bf16 v[102:105], v[146:149], v[184:187], v[102:105]
	v_mfma_f32_16x16x32_bf16 v[94:97], v[154:157], v[184:187], v[94:97]
	v_mfma_f32_16x16x32_bf16 v[86:89], v[146:149], v[202:205], v[86:89]
	v_mfma_f32_16x16x32_bf16 v[78:81], v[154:157], v[202:205], v[78:81]
	v_mfma_f32_16x16x32_bf16 v[70:73], v[146:149], v[210:213], v[70:73]
	v_mfma_f32_16x16x32_bf16 v[66:69], v[154:157], v[210:213], v[66:69]
	v_mfma_f32_16x16x32_bf16 v[118:121], v[150:153], v[180:183], v[118:121]
	v_mfma_f32_16x16x32_bf16 v[114:117], v[158:161], v[180:183], v[114:117]
	v_mfma_f32_16x16x32_bf16 v[102:105], v[150:153], v[190:193], v[102:105]
	v_mfma_f32_16x16x32_bf16 v[94:97], v[158:161], v[190:193], v[94:97]
	v_mfma_f32_16x16x32_bf16 v[86:89], v[150:153], v[206:209], v[86:89]
	v_mfma_f32_16x16x32_bf16 v[78:81], v[158:161], v[206:209], v[78:81]
	v_mfma_f32_16x16x32_bf16 v[70:73], v[150:153], v[214:217], v[70:73]
	v_mfma_f32_16x16x32_bf16 v[66:69], v[158:161], v[214:217], v[66:69]
	s_barrier
	s_setprio 0
	s_add_i32 s0, s78, s26
	v_lshl_add_u64 v[194:195], v[194:195], 0, s[16:17]
	s_mov_b32 m0, s0
	ds_read_b128 v[162:165], v189 offset:49152
	ds_read_b128 v[180:183], v189 offset:50176
	ds_read_b128 v[184:187], v189 offset:51200
	ds_read_b128 v[190:193], v189 offset:52224
	ds_read_b128 v[202:205], v189 offset:53248
	ds_read_b128 v[206:209], v189 offset:54272
	ds_read_b128 v[210:213], v189 offset:55296
	ds_read_b128 v[214:217], v189 offset:56320
	global_load_lds_dwordx4 v[194:195], off
	s_add_i32 m0, s0, 0x2000
	s_add_u32 s0, s8, 0x80080
	v_lshl_add_u64 v[194:195], v[218:219], 0, s[16:17]
	s_addc_u32 s1, s9, 0
	s_add_i32 s8, s79, s26
	global_load_lds_dwordx4 v[194:195], off
	v_lshl_add_u64 v[194:195], s[0:1], 0, v[196:197]
	s_mov_b32 m0, s8
	s_nop 0
	global_load_lds_dwordx4 v[194:195], off
	v_lshl_add_u64 v[194:195], s[0:1], 0, v[170:171]
	s_add_i32 m0, s8, 0x2000
	s_nop 0
	global_load_lds_dwordx4 v[194:195], off
	v_lshl_add_u64 v[194:195], v[220:221], 0, s[16:17]
	s_mov_b32 m0, s35
	s_nop 0
	global_load_lds_dwordx4 v[194:195], off
	v_lshl_add_u64 v[194:195], v[222:223], 0, s[16:17]
	s_mov_b32 m0, s53
	s_nop 0
	global_load_lds_dwordx4 v[194:195], off
	s_waitcnt vmcnt(8)
	s_waitcnt lgkmcnt(0)
	s_setprio 1
	s_barrier
	v_mfma_f32_16x16x32_bf16 v[62:65], v[130:133], v[162:165], v[62:65]
	v_mfma_f32_16x16x32_bf16 v[58:61], v[138:141], v[162:165], v[58:61]
	v_mfma_f32_16x16x32_bf16 v[50:53], v[130:133], v[184:187], v[50:53]
	v_mfma_f32_16x16x32_bf16 v[42:45], v[138:141], v[184:187], v[42:45]
	v_mfma_f32_16x16x32_bf16 v[34:37], v[130:133], v[202:205], v[34:37]
	v_mfma_f32_16x16x32_bf16 v[26:29], v[138:141], v[202:205], v[26:29]
	v_mfma_f32_16x16x32_bf16 v[18:21], v[130:133], v[210:213], v[18:21]
	v_mfma_f32_16x16x32_bf16 v[10:13], v[138:141], v[210:213], v[10:13]
	v_mfma_f32_16x16x32_bf16 v[62:65], v[134:137], v[180:183], v[62:65]
	v_mfma_f32_16x16x32_bf16 v[58:61], v[142:145], v[180:183], v[58:61]
	v_mfma_f32_16x16x32_bf16 v[50:53], v[134:137], v[190:193], v[50:53]
	v_mfma_f32_16x16x32_bf16 v[42:45], v[142:145], v[190:193], v[42:45]
	v_mfma_f32_16x16x32_bf16 v[34:37], v[134:137], v[206:209], v[34:37]
	v_mfma_f32_16x16x32_bf16 v[26:29], v[142:145], v[206:209], v[26:29]
	v_mfma_f32_16x16x32_bf16 v[18:21], v[134:137], v[214:217], v[18:21]
	v_mfma_f32_16x16x32_bf16 v[10:13], v[142:145], v[214:217], v[10:13]
	v_mfma_f32_16x16x32_bf16 v[54:57], v[146:149], v[162:165], v[54:57]
	v_mfma_f32_16x16x32_bf16 v[46:49], v[154:157], v[162:165], v[46:49]
	v_mfma_f32_16x16x32_bf16 v[38:41], v[146:149], v[184:187], v[38:41]
	v_mfma_f32_16x16x32_bf16 v[30:33], v[154:157], v[184:187], v[30:33]
	v_mfma_f32_16x16x32_bf16 v[22:25], v[146:149], v[202:205], v[22:25]
	v_mfma_f32_16x16x32_bf16 v[14:17], v[154:157], v[202:205], v[14:17]
	v_mfma_f32_16x16x32_bf16 v[6:9], v[146:149], v[210:213], v[6:9]
	v_mfma_f32_16x16x32_bf16 v[2:5], v[154:157], v[210:213], v[2:5]
	v_mfma_f32_16x16x32_bf16 v[54:57], v[150:153], v[180:183], v[54:57]
	v_mfma_f32_16x16x32_bf16 v[46:49], v[158:161], v[180:183], v[46:49]
	v_mfma_f32_16x16x32_bf16 v[38:41], v[150:153], v[190:193], v[38:41]
	v_mfma_f32_16x16x32_bf16 v[30:33], v[158:161], v[190:193], v[30:33]
	v_mfma_f32_16x16x32_bf16 v[22:25], v[150:153], v[206:209], v[22:25]
	v_mfma_f32_16x16x32_bf16 v[14:17], v[158:161], v[206:209], v[14:17]
	v_mfma_f32_16x16x32_bf16 v[6:9], v[150:153], v[214:217], v[6:9]
	v_mfma_f32_16x16x32_bf16 v[2:5], v[158:161], v[214:217], v[2:5]
	s_barrier
	s_setprio 0
	s_add_u32 s72, s72, 0x100
	s_addc_u32 s73, s73, 0
	s_add_u32 s62, s62, 0x100
	s_addc_u32 s63, s63, 0
	s_cmp_ge_i32 s77, s69
	s_mov_b32 s8, s77
	s_cbranch_scc0 .LBB0_2357
	s_and_b64 vcc, exec, s[38:39]
	s_cbranch_vccz .LBB0_2360
	s_barrier

.LBB0_2507:
	s_add_i32 s69, s8, 2
	s_add_u32 s0, s52, 0xfff80080
	s_addc_u32 s1, s53, -1
	s_add_i32 s70, 0, 0x10000
	s_cmp_eq_u32 s66, s8
	s_cselect_b32 s59, s41, s1
	s_cselect_b32 s58, s45, s0
	s_cselect_b32 s9, s43, s68
	s_cselect_b32 s8, s65, s67
	s_add_i32 s71, 0, 0x14000
	v_add_u32_e32 v156, s70, v141
	v_add_u32_e32 v172, s71, v141
	ds_read_b128 v[144:147], v156
	ds_read_b128 v[148:151], v156 offset:1024
	ds_read_b128 v[152:155], v156 offset:2048
	ds_read_b128 v[156:159], v156 offset:3072
	ds_read_b128 v[160:163], v172
	ds_read_b128 v[164:167], v172 offset:1024
	ds_read_b128 v[168:171], v172 offset:2048
	ds_read_b128 v[172:175], v172 offset:3072
	v_lshl_add_u64 v[214:215], s[52:53], 0, v[138:139]
	s_add_i32 m0, s27, 0xc000
	ds_read_b128 v[176:179], v143
	ds_read_b128 v[180:183], v143 offset:1024
	ds_read_b128 v[184:187], v143 offset:2048
	ds_read_b128 v[188:191], v143 offset:3072
	ds_read_b128 v[192:195], v143 offset:4096
	ds_read_b128 v[202:205], v143 offset:5120
	ds_read_b128 v[206:209], v143 offset:6144
	ds_read_b128 v[210:213], v143 offset:7168
	global_load_lds_dwordx4 v[214:215], off
	v_lshl_add_u64 v[214:215], s[52:53], 0, v[136:137]
	s_add_i32 m0, s27, 0xe000
	s_nop 0
	global_load_lds_dwordx4 v[214:215], off
	s_waitcnt vmcnt(8)
	s_waitcnt lgkmcnt(0)
	s_setprio 1
	s_barrier
	v_mfma_f32_16x16x32_bf16 v[126:129], v[144:147], v[176:179], v[126:129]
	v_mfma_f32_16x16x32_bf16 v[118:121], v[152:155], v[176:179], v[118:121]
	v_mfma_f32_16x16x32_bf16 v[110:113], v[144:147], v[184:187], v[110:113]
	v_mfma_f32_16x16x32_bf16 v[102:105], v[152:155], v[184:187], v[102:105]
	v_mfma_f32_16x16x32_bf16 v[94:97], v[144:147], v[192:195], v[94:97]
	v_mfma_f32_16x16x32_bf16 v[86:89], v[152:155], v[192:195], v[86:89]
	v_mfma_f32_16x16x32_bf16 v[78:81], v[144:147], v[206:209], v[78:81]
	v_mfma_f32_16x16x32_bf16 v[70:73], v[152:155], v[206:209], v[70:73]
	v_mfma_f32_16x16x32_bf16 v[126:129], v[148:151], v[180:183], v[126:129]
	v_mfma_f32_16x16x32_bf16 v[118:121], v[156:159], v[180:183], v[118:121]
	v_mfma_f32_16x16x32_bf16 v[110:113], v[148:151], v[188:191], v[110:113]
	v_mfma_f32_16x16x32_bf16 v[102:105], v[156:159], v[188:191], v[102:105]
	v_mfma_f32_16x16x32_bf16 v[94:97], v[148:151], v[202:205], v[94:97]
	v_mfma_f32_16x16x32_bf16 v[86:89], v[156:159], v[202:205], v[86:89]
	v_mfma_f32_16x16x32_bf16 v[78:81], v[148:151], v[210:213], v[78:81]
	v_mfma_f32_16x16x32_bf16 v[70:73], v[156:159], v[210:213], v[70:73]
	v_mfma_f32_16x16x32_bf16 v[122:125], v[160:163], v[176:179], v[122:125]
	v_mfma_f32_16x16x32_bf16 v[114:117], v[168:171], v[176:179], v[114:117]
	v_mfma_f32_16x16x32_bf16 v[106:109], v[160:163], v[184:187], v[106:109]
	v_mfma_f32_16x16x32_bf16 v[98:101], v[168:171], v[184:187], v[98:101]
	v_mfma_f32_16x16x32_bf16 v[90:93], v[160:163], v[192:195], v[90:93]
	v_mfma_f32_16x16x32_bf16 v[82:85], v[168:171], v[192:195], v[82:85]
	v_mfma_f32_16x16x32_bf16 v[74:77], v[160:163], v[206:209], v[74:77]
	v_mfma_f32_16x16x32_bf16 v[66:69], v[168:171], v[206:209], v[66:69]
	v_mfma_f32_16x16x32_bf16 v[122:125], v[164:167], v[180:183], v[122:125]
	v_mfma_f32_16x16x32_bf16 v[114:117], v[172:175], v[180:183], v[114:117]
	v_mfma_f32_16x16x32_bf16 v[106:109], v[164:167], v[188:191], v[106:109]
	v_mfma_f32_16x16x32_bf16 v[98:101], v[172:175], v[188:191], v[98:101]
	v_mfma_f32_16x16x32_bf16 v[90:93], v[164:167], v[202:205], v[90:93]
	v_mfma_f32_16x16x32_bf16 v[82:85], v[172:175], v[202:205], v[82:85]
	v_mfma_f32_16x16x32_bf16 v[74:77], v[164:167], v[210:213], v[74:77]
	v_mfma_f32_16x16x32_bf16 v[66:69], v[172:175], v[210:213], v[66:69]
	s_barrier
	s_setprio 0
	s_add_i32 s0, s70, s26
	v_lshl_add_u64 v[214:215], s[8:9], 0, v[196:197]
	s_mov_b32 m0, s0
	ds_read_b128 v[176:179], v143 offset:16384
	ds_read_b128 v[180:183], v143 offset:17408
	ds_read_b128 v[184:187], v143 offset:18432
	ds_read_b128 v[188:191], v143 offset:19456
	ds_read_b128 v[192:195], v143 offset:20480
	ds_read_b128 v[202:205], v143 offset:21504
	ds_read_b128 v[206:209], v143 offset:22528
	ds_read_b128 v[210:213], v143 offset:23552
	global_load_lds_dwordx4 v[214:215], off
	s_add_i32 m0, s0, 0x2000
	s_add_u32 s0, s8, 0x80000
	v_lshl_add_u64 v[216:217], s[8:9], 0, v[130:131]
	s_addc_u32 s1, s9, 0
	s_add_i32 s70, s71, s26
	global_load_lds_dwordx4 v[216:217], off
	v_lshl_add_u64 v[218:219], s[0:1], 0, v[196:197]
	s_mov_b32 m0, s70
	v_lshl_add_u64 v[220:221], s[58:59], 0, v[132:133]
	global_load_lds_dwordx4 v[218:219], off
	v_lshl_add_u64 v[218:219], s[0:1], 0, v[130:131]
	s_add_i32 m0, s70, 0x2000
	s_nop 0
	global_load_lds_dwordx4 v[218:219], off
	v_lshl_add_u64 v[218:219], s[58:59], 0, v[134:135]
	s_mov_b32 m0, s27
	s_nop 0
	global_load_lds_dwordx4 v[218:219], off
	s_mov_b32 m0, s28
	s_nop 0
	global_load_lds_dwordx4 v[220:221], off
	s_waitcnt vmcnt(8)
	s_waitcnt lgkmcnt(0)
	s_setprio 1
	s_barrier
	v_mfma_f32_16x16x32_bf16 v[62:65], v[144:147], v[176:179], v[62:65]
	v_mfma_f32_16x16x32_bf16 v[54:57], v[152:155], v[176:179], v[54:57]
	v_mfma_f32_16x16x32_bf16 v[46:49], v[144:147], v[184:187], v[46:49]
	v_mfma_f32_16x16x32_bf16 v[38:41], v[152:155], v[184:187], v[38:41]
	v_mfma_f32_16x16x32_bf16 v[30:33], v[144:147], v[192:195], v[30:33]
	v_mfma_f32_16x16x32_bf16 v[22:25], v[152:155], v[192:195], v[22:25]
	v_mfma_f32_16x16x32_bf16 v[14:17], v[144:147], v[206:209], v[14:17]
	v_mfma_f32_16x16x32_bf16 v[6:9], v[152:155], v[206:209], v[6:9]
	v_mfma_f32_16x16x32_bf16 v[62:65], v[148:151], v[180:183], v[62:65]
	v_mfma_f32_16x16x32_bf16 v[54:57], v[156:159], v[180:183], v[54:57]
	v_mfma_f32_16x16x32_bf16 v[46:49], v[148:151], v[188:191], v[46:49]
	v_mfma_f32_16x16x32_bf16 v[38:41], v[156:159], v[188:191], v[38:41]
	v_mfma_f32_16x16x32_bf16 v[30:33], v[148:151], v[202:205], v[30:33]
	v_mfma_f32_16x16x32_bf16 v[22:25], v[156:159], v[202:205], v[22:25]
	v_mfma_f32_16x16x32_bf16 v[14:17], v[148:151], v[210:213], v[14:17]
	v_mfma_f32_16x16x32_bf16 v[6:9], v[156:159], v[210:213], v[6:9]
	v_mfma_f32_16x16x32_bf16 v[58:61], v[160:163], v[176:179], v[58:61]
	v_mfma_f32_16x16x32_bf16 v[50:53], v[168:171], v[176:179], v[50:53]
	v_mfma_f32_16x16x32_bf16 v[42:45], v[160:163], v[184:187], v[42:45]
	v_mfma_f32_16x16x32_bf16 v[34:37], v[168:171], v[184:187], v[34:37]
	v_mfma_f32_16x16x32_bf16 v[26:29], v[160:163], v[192:195], v[26:29]
	v_mfma_f32_16x16x32_bf16 v[18:21], v[168:171], v[192:195], v[18:21]
	v_mfma_f32_16x16x32_bf16 v[10:13], v[160:163], v[206:209], v[10:13]
	v_mfma_f32_16x16x32_bf16 v[2:5], v[168:171], v[206:209], v[2:5]
	v_mfma_f32_16x16x32_bf16 v[58:61], v[164:167], v[180:183], v[58:61]
	v_mfma_f32_16x16x32_bf16 v[50:53], v[172:175], v[180:183], v[50:53]
	v_mfma_f32_16x16x32_bf16 v[42:45], v[164:167], v[188:191], v[42:45]
	v_mfma_f32_16x16x32_bf16 v[34:37], v[172:175], v[188:191], v[34:37]
	v_mfma_f32_16x16x32_bf16 v[26:29], v[164:167], v[202:205], v[26:29]
	v_mfma_f32_16x16x32_bf16 v[18:21], v[172:175], v[202:205], v[18:21]
	v_mfma_f32_16x16x32_bf16 v[10:13], v[164:167], v[210:213], v[10:13]
	v_mfma_f32_16x16x32_bf16 v[2:5], v[172:175], v[210:213], v[2:5]
	s_barrier
	s_setprio 0
	s_add_i32 s70, 0, 0x18000
	s_add_i32 s71, 0, 0x1c000
	v_add_u32_e32 v156, s70, v141
	v_add_u32_e32 v172, s71, v141
	ds_read_b128 v[144:147], v156
	ds_read_b128 v[148:151], v156 offset:1024
	ds_read_b128 v[152:155], v156 offset:2048
	ds_read_b128 v[156:159], v156 offset:3072
	ds_read_b128 v[160:163], v172
	ds_read_b128 v[164:167], v172 offset:1024
	ds_read_b128 v[168:171], v172 offset:2048
	ds_read_b128 v[172:175], v172 offset:3072
	s_add_u32 s0, s58, 0x80000
	s_addc_u32 s1, s59, 0
	s_mov_b32 m0, s29
	v_lshl_add_u64 v[222:223], s[0:1], 0, v[134:135]
	ds_read_b128 v[176:179], v143 offset:32768
	ds_read_b128 v[180:183], v143 offset:33792
	ds_read_b128 v[184:187], v143 offset:34816
	ds_read_b128 v[188:191], v143 offset:35840
	ds_read_b128 v[192:195], v143 offset:36864
	ds_read_b128 v[202:205], v143 offset:37888
	ds_read_b128 v[206:209], v143 offset:38912
	ds_read_b128 v[210:213], v143 offset:39936
	global_load_lds_dwordx4 v[222:223], off
	v_lshl_add_u64 v[222:223], s[0:1], 0, v[132:133]
	s_mov_b32 m0, s30
	s_nop 0
	global_load_lds_dwordx4 v[222:223], off
	s_waitcnt vmcnt(8)
	s_waitcnt lgkmcnt(0)
	s_setprio 1
	s_barrier
	v_mfma_f32_16x16x32_bf16 v[126:129], v[144:147], v[176:179], v[126:129]
	v_mfma_f32_16x16x32_bf16 v[118:121], v[152:155], v[176:179], v[118:121]
	v_mfma_f32_16x16x32_bf16 v[110:113], v[144:147], v[184:187], v[110:113]
	v_mfma_f32_16x16x32_bf16 v[102:105], v[152:155], v[184:187], v[102:105]
	v_mfma_f32_16x16x32_bf16 v[94:97], v[144:147], v[192:195], v[94:97]
	v_mfma_f32_16x16x32_bf16 v[86:89], v[152:155], v[192:195], v[86:89]
	v_mfma_f32_16x16x32_bf16 v[78:81], v[144:147], v[206:209], v[78:81]
	v_mfma_f32_16x16x32_bf16 v[70:73], v[152:155], v[206:209], v[70:73]
	v_mfma_f32_16x16x32_bf16 v[126:129], v[148:151], v[180:183], v[126:129]
	v_mfma_f32_16x16x32_bf16 v[118:121], v[156:159], v[180:183], v[118:121]
	v_mfma_f32_16x16x32_bf16 v[110:113], v[148:151], v[188:191], v[110:113]
	v_mfma_f32_16x16x32_bf16 v[102:105], v[156:159], v[188:191], v[102:105]
	v_mfma_f32_16x16x32_bf16 v[94:97], v[148:151], v[202:205], v[94:97]
	v_mfma_f32_16x16x32_bf16 v[86:89], v[156:159], v[202:205], v[86:89]
	v_mfma_f32_16x16x32_bf16 v[78:81], v[148:151], v[210:213], v[78:81]
	v_mfma_f32_16x16x32_bf16 v[70:73], v[156:159], v[210:213], v[70:73]
	v_mfma_f32_16x16x32_bf16 v[122:125], v[160:163], v[176:179], v[122:125]
	v_mfma_f32_16x16x32_bf16 v[114:117], v[168:171], v[176:179], v[114:117]
	v_mfma_f32_16x16x32_bf16 v[106:109], v[160:163], v[184:187], v[106:109]
	v_mfma_f32_16x16x32_bf16 v[98:101], v[168:171], v[184:187], v[98:101]
	v_mfma_f32_16x16x32_bf16 v[90:93], v[160:163], v[192:195], v[90:93]
	v_mfma_f32_16x16x32_bf16 v[82:85], v[168:171], v[192:195], v[82:85]
	v_mfma_f32_16x16x32_bf16 v[74:77], v[160:163], v[206:209], v[74:77]
	v_mfma_f32_16x16x32_bf16 v[66:69], v[168:171], v[206:209], v[66:69]
	v_mfma_f32_16x16x32_bf16 v[122:125], v[164:167], v[180:183], v[122:125]
	v_mfma_f32_16x16x32_bf16 v[114:117], v[172:175], v[180:183], v[114:117]
	v_mfma_f32_16x16x32_bf16 v[106:109], v[164:167], v[188:191], v[106:109]
	v_mfma_f32_16x16x32_bf16 v[98:101], v[172:175], v[188:191], v[98:101]
	v_mfma_f32_16x16x32_bf16 v[90:93], v[164:167], v[202:205], v[90:93]
	v_mfma_f32_16x16x32_bf16 v[82:85], v[172:175], v[202:205], v[82:85]
	v_mfma_f32_16x16x32_bf16 v[74:77], v[164:167], v[210:213], v[74:77]
	v_mfma_f32_16x16x32_bf16 v[66:69], v[172:175], v[210:213], v[66:69]
	s_barrier
	s_setprio 0
	s_add_i32 s0, s70, s26
	v_lshl_add_u64 v[214:215], v[214:215], 0, s[16:17]
	s_mov_b32 m0, s0
	ds_read_b128 v[176:179], v143 offset:49152
	ds_read_b128 v[180:183], v143 offset:50176
	ds_read_b128 v[184:187], v143 offset:51200
	ds_read_b128 v[188:191], v143 offset:52224
	ds_read_b128 v[192:195], v143 offset:53248
	ds_read_b128 v[202:205], v143 offset:54272
	ds_read_b128 v[206:209], v143 offset:55296
	ds_read_b128 v[210:213], v143 offset:56320
	global_load_lds_dwordx4 v[214:215], off
	s_add_i32 m0, s0, 0x2000
	s_add_u32 s0, s8, 0x80080
	v_lshl_add_u64 v[214:215], v[216:217], 0, s[16:17]
	s_addc_u32 s1, s9, 0
	s_add_i32 s8, s71, s26
	global_load_lds_dwordx4 v[214:215], off
	v_lshl_add_u64 v[214:215], s[0:1], 0, v[196:197]
	s_mov_b32 m0, s8
	s_nop 0
	global_load_lds_dwordx4 v[214:215], off
	v_lshl_add_u64 v[214:215], s[0:1], 0, v[130:131]
	s_add_i32 m0, s8, 0x2000
	s_nop 0
	global_load_lds_dwordx4 v[214:215], off
	v_lshl_add_u64 v[214:215], v[218:219], 0, s[16:17]
	s_mov_b32 m0, s31
	s_nop 0
	global_load_lds_dwordx4 v[214:215], off
	v_lshl_add_u64 v[214:215], v[220:221], 0, s[16:17]
	s_mov_b32 m0, s34
	s_nop 0
	global_load_lds_dwordx4 v[214:215], off
	s_waitcnt vmcnt(8)
	s_waitcnt lgkmcnt(0)
	s_setprio 1
	s_barrier
	v_mfma_f32_16x16x32_bf16 v[62:65], v[144:147], v[176:179], v[62:65]
	v_mfma_f32_16x16x32_bf16 v[54:57], v[152:155], v[176:179], v[54:57]
	v_mfma_f32_16x16x32_bf16 v[46:49], v[144:147], v[184:187], v[46:49]
	v_mfma_f32_16x16x32_bf16 v[38:41], v[152:155], v[184:187], v[38:41]
	v_mfma_f32_16x16x32_bf16 v[30:33], v[144:147], v[192:195], v[30:33]
	v_mfma_f32_16x16x32_bf16 v[22:25], v[152:155], v[192:195], v[22:25]
	v_mfma_f32_16x16x32_bf16 v[14:17], v[144:147], v[206:209], v[14:17]
	v_mfma_f32_16x16x32_bf16 v[6:9], v[152:155], v[206:209], v[6:9]
	v_mfma_f32_16x16x32_bf16 v[62:65], v[148:151], v[180:183], v[62:65]
	v_mfma_f32_16x16x32_bf16 v[54:57], v[156:159], v[180:183], v[54:57]
	v_mfma_f32_16x16x32_bf16 v[46:49], v[148:151], v[188:191], v[46:49]
	v_mfma_f32_16x16x32_bf16 v[38:41], v[156:159], v[188:191], v[38:41]
	v_mfma_f32_16x16x32_bf16 v[30:33], v[148:151], v[202:205], v[30:33]
	v_mfma_f32_16x16x32_bf16 v[22:25], v[156:159], v[202:205], v[22:25]
	v_mfma_f32_16x16x32_bf16 v[14:17], v[148:151], v[210:213], v[14:17]
	v_mfma_f32_16x16x32_bf16 v[6:9], v[156:159], v[210:213], v[6:9]
	v_mfma_f32_16x16x32_bf16 v[58:61], v[160:163], v[176:179], v[58:61]
	v_mfma_f32_16x16x32_bf16 v[50:53], v[168:171], v[176:179], v[50:53]
	v_mfma_f32_16x16x32_bf16 v[42:45], v[160:163], v[184:187], v[42:45]
	v_mfma_f32_16x16x32_bf16 v[34:37], v[168:171], v[184:187], v[34:37]
	v_mfma_f32_16x16x32_bf16 v[26:29], v[160:163], v[192:195], v[26:29]
	v_mfma_f32_16x16x32_bf16 v[18:21], v[168:171], v[192:195], v[18:21]
	v_mfma_f32_16x16x32_bf16 v[10:13], v[160:163], v[206:209], v[10:13]
	v_mfma_f32_16x16x32_bf16 v[2:5], v[168:171], v[206:209], v[2:5]
	v_mfma_f32_16x16x32_bf16 v[58:61], v[164:167], v[180:183], v[58:61]
	v_mfma_f32_16x16x32_bf16 v[50:53], v[172:175], v[180:183], v[50:53]
	v_mfma_f32_16x16x32_bf16 v[42:45], v[164:167], v[188:191], v[42:45]
	v_mfma_f32_16x16x32_bf16 v[34:37], v[172:175], v[188:191], v[34:37]
	v_mfma_f32_16x16x32_bf16 v[26:29], v[164:167], v[202:205], v[26:29]
	v_mfma_f32_16x16x32_bf16 v[18:21], v[172:175], v[202:205], v[18:21]
	v_mfma_f32_16x16x32_bf16 v[10:13], v[164:167], v[210:213], v[10:13]
	v_mfma_f32_16x16x32_bf16 v[2:5], v[172:175], v[210:213], v[2:5]
	s_barrier
	s_setprio 0
	s_add_u32 s67, s67, 0x100
	s_addc_u32 s68, s68, 0
	s_add_u32 s52, s52, 0x100
	s_addc_u32 s53, s53, 0
	s_cmp_ge_i32 s69, s62
	s_mov_b32 s8, s69
	s_cbranch_scc0 .LBB0_2507
	s_and_b64 vcc, exec, s[38:39]
	s_cbranch_vccz .LBB0_2510
	s_barrier

.LBB0_2588:
	s_add_i32 s72, s48, 2
	s_add_u32 s8, s46, 0x100
	s_addc_u32 s9, s47, 0
	s_add_i32 s0, 0, 0x10000
	s_cmp_eq_u32 s41, s48
	s_cselect_b32 s51, s43, s9
	s_cselect_b32 s50, s42, s8
	s_cselect_b32 s49, s45, s71
	s_cselect_b32 s48, s44, s70
	s_add_i32 s73, 0, 0x14000
	v_add_u32_e32 v142, s0, v188
	v_add_u32_e32 v172, s73, v188
	ds_read_b128 v[130:133], v142
	ds_read_b128 v[134:137], v142 offset:1024
	ds_read_b128 v[138:141], v142 offset:2048
	ds_read_b128 v[142:145], v142 offset:3072
	ds_read_b128 v[146:149], v172
	ds_read_b128 v[164:167], v172 offset:1024
	ds_read_b128 v[168:171], v172 offset:2048
	ds_read_b128 v[172:175], v172 offset:3072
	v_lshl_add_u64 v[194:195], s[46:47], 0, v[162:163]
	s_add_i32 m0, s27, 0xc000
	ds_read_b128 v[176:179], v189
	ds_read_b128 v[180:183], v189 offset:1024
	ds_read_b128 v[184:187], v189 offset:2048
	ds_read_b128 v[190:193], v189 offset:3072
	ds_read_b128 v[202:205], v189 offset:4096
	ds_read_b128 v[206:209], v189 offset:5120
	ds_read_b128 v[210:213], v189 offset:6144
	ds_read_b128 v[214:217], v189 offset:7168
	global_load_lds_dwordx4 v[194:195], off
	v_lshl_add_u64 v[194:195], s[46:47], 0, v[160:161]
	s_add_i32 m0, s27, 0xe000
	s_nop 0
	global_load_lds_dwordx4 v[194:195], off
	s_waitcnt vmcnt(8)
	s_waitcnt lgkmcnt(0)
	s_setprio 1
	s_barrier
	v_mfma_f32_16x16x32_bf16 v[126:129], v[130:133], v[176:179], v[126:129]
	v_mfma_f32_16x16x32_bf16 v[122:125], v[138:141], v[176:179], v[122:125]
	v_mfma_f32_16x16x32_bf16 v[110:113], v[130:133], v[184:187], v[110:113]
	v_mfma_f32_16x16x32_bf16 v[106:109], v[138:141], v[184:187], v[106:109]
	v_mfma_f32_16x16x32_bf16 v[98:101], v[130:133], v[202:205], v[98:101]
	v_mfma_f32_16x16x32_bf16 v[90:93], v[138:141], v[202:205], v[90:93]
	v_mfma_f32_16x16x32_bf16 v[82:85], v[130:133], v[210:213], v[82:85]
	v_mfma_f32_16x16x32_bf16 v[74:77], v[138:141], v[210:213], v[74:77]
	v_mfma_f32_16x16x32_bf16 v[126:129], v[134:137], v[180:183], v[126:129]
	v_mfma_f32_16x16x32_bf16 v[122:125], v[142:145], v[180:183], v[122:125]
	v_mfma_f32_16x16x32_bf16 v[110:113], v[134:137], v[190:193], v[110:113]
	v_mfma_f32_16x16x32_bf16 v[106:109], v[142:145], v[190:193], v[106:109]
	v_mfma_f32_16x16x32_bf16 v[98:101], v[134:137], v[206:209], v[98:101]
	v_mfma_f32_16x16x32_bf16 v[90:93], v[142:145], v[206:209], v[90:93]
	v_mfma_f32_16x16x32_bf16 v[82:85], v[134:137], v[214:217], v[82:85]
	v_mfma_f32_16x16x32_bf16 v[74:77], v[142:145], v[214:217], v[74:77]
	v_mfma_f32_16x16x32_bf16 v[118:121], v[146:149], v[176:179], v[118:121]
	v_mfma_f32_16x16x32_bf16 v[114:117], v[168:171], v[176:179], v[114:117]
	v_mfma_f32_16x16x32_bf16 v[102:105], v[146:149], v[184:187], v[102:105]
	v_mfma_f32_16x16x32_bf16 v[94:97], v[168:171], v[184:187], v[94:97]
	v_mfma_f32_16x16x32_bf16 v[86:89], v[146:149], v[202:205], v[86:89]
	v_mfma_f32_16x16x32_bf16 v[78:81], v[168:171], v[202:205], v[78:81]
	v_mfma_f32_16x16x32_bf16 v[70:73], v[146:149], v[210:213], v[70:73]
	v_mfma_f32_16x16x32_bf16 v[66:69], v[168:171], v[210:213], v[66:69]
	v_mfma_f32_16x16x32_bf16 v[118:121], v[164:167], v[180:183], v[118:121]
	v_mfma_f32_16x16x32_bf16 v[114:117], v[172:175], v[180:183], v[114:117]
	v_mfma_f32_16x16x32_bf16 v[102:105], v[164:167], v[190:193], v[102:105]
	v_mfma_f32_16x16x32_bf16 v[94:97], v[172:175], v[190:193], v[94:97]
	v_mfma_f32_16x16x32_bf16 v[86:89], v[164:167], v[206:209], v[86:89]
	v_mfma_f32_16x16x32_bf16 v[78:81], v[172:175], v[206:209], v[78:81]
	v_mfma_f32_16x16x32_bf16 v[70:73], v[164:167], v[214:217], v[70:73]
	v_mfma_f32_16x16x32_bf16 v[66:69], v[172:175], v[214:217], v[66:69]
	s_barrier
	s_setprio 0
	s_add_i32 s0, s0, s26
	v_lshl_add_u64 v[194:195], s[48:49], 0, v[196:197]
	s_mov_b32 m0, s0
	ds_read_b128 v[176:179], v189 offset:16384
	ds_read_b128 v[180:183], v189 offset:17408
	ds_read_b128 v[184:187], v189 offset:18432
	ds_read_b128 v[190:193], v189 offset:19456
	ds_read_b128 v[202:205], v189 offset:20480
	ds_read_b128 v[206:209], v189 offset:21504
	ds_read_b128 v[210:213], v189 offset:22528
	ds_read_b128 v[214:217], v189 offset:23552
	global_load_lds_dwordx4 v[194:195], off
	s_add_i32 m0, s0, 0x2000
	s_add_u32 s0, s48, 0x158000
	v_lshl_add_u64 v[218:219], s[48:49], 0, v[154:155]
	s_addc_u32 s1, s49, 0
	s_add_i32 s46, s73, s26
	global_load_lds_dwordx4 v[218:219], off
	v_lshl_add_u64 v[220:221], s[0:1], 0, v[196:197]
	s_mov_b32 m0, s46
	v_lshl_add_u64 v[222:223], s[50:51], 0, v[152:153]
	global_load_lds_dwordx4 v[220:221], off
	v_lshl_add_u64 v[220:221], s[0:1], 0, v[154:155]
	s_add_i32 m0, s46, 0x2000
	s_nop 0
	global_load_lds_dwordx4 v[220:221], off
	v_lshl_add_u64 v[220:221], s[50:51], 0, v[150:151]
	s_mov_b32 m0, s27
	s_nop 0
	global_load_lds_dwordx4 v[220:221], off
	s_mov_b32 m0, s30
	s_nop 0
	global_load_lds_dwordx4 v[222:223], off
	s_waitcnt vmcnt(8)
	s_waitcnt lgkmcnt(0)
	s_setprio 1
	s_barrier
	v_mfma_f32_16x16x32_bf16 v[62:65], v[130:133], v[176:179], v[62:65]
	v_mfma_f32_16x16x32_bf16 v[58:61], v[138:141], v[176:179], v[58:61]
	v_mfma_f32_16x16x32_bf16 v[50:53], v[130:133], v[184:187], v[50:53]
	v_mfma_f32_16x16x32_bf16 v[42:45], v[138:141], v[184:187], v[42:45]
	v_mfma_f32_16x16x32_bf16 v[34:37], v[130:133], v[202:205], v[34:37]
	v_mfma_f32_16x16x32_bf16 v[26:29], v[138:141], v[202:205], v[26:29]
	v_mfma_f32_16x16x32_bf16 v[18:21], v[130:133], v[210:213], v[18:21]
	v_mfma_f32_16x16x32_bf16 v[10:13], v[138:141], v[210:213], v[10:13]
	v_mfma_f32_16x16x32_bf16 v[62:65], v[134:137], v[180:183], v[62:65]
	v_mfma_f32_16x16x32_bf16 v[58:61], v[142:145], v[180:183], v[58:61]
	v_mfma_f32_16x16x32_bf16 v[50:53], v[134:137], v[190:193], v[50:53]
	v_mfma_f32_16x16x32_bf16 v[42:45], v[142:145], v[190:193], v[42:45]
	v_mfma_f32_16x16x32_bf16 v[34:37], v[134:137], v[206:209], v[34:37]
	v_mfma_f32_16x16x32_bf16 v[26:29], v[142:145], v[206:209], v[26:29]
	v_mfma_f32_16x16x32_bf16 v[18:21], v[134:137], v[214:217], v[18:21]
	v_mfma_f32_16x16x32_bf16 v[10:13], v[142:145], v[214:217], v[10:13]
	v_mfma_f32_16x16x32_bf16 v[54:57], v[146:149], v[176:179], v[54:57]
	v_mfma_f32_16x16x32_bf16 v[46:49], v[168:171], v[176:179], v[46:49]
	v_mfma_f32_16x16x32_bf16 v[38:41], v[146:149], v[184:187], v[38:41]
	v_mfma_f32_16x16x32_bf16 v[30:33], v[168:171], v[184:187], v[30:33]
	v_mfma_f32_16x16x32_bf16 v[22:25], v[146:149], v[202:205], v[22:25]
	v_mfma_f32_16x16x32_bf16 v[14:17], v[168:171], v[202:205], v[14:17]
	v_mfma_f32_16x16x32_bf16 v[6:9], v[146:149], v[210:213], v[6:9]
	v_mfma_f32_16x16x32_bf16 v[2:5], v[168:171], v[210:213], v[2:5]
	v_mfma_f32_16x16x32_bf16 v[54:57], v[164:167], v[180:183], v[54:57]
	v_mfma_f32_16x16x32_bf16 v[46:49], v[172:175], v[180:183], v[46:49]
	v_mfma_f32_16x16x32_bf16 v[38:41], v[164:167], v[190:193], v[38:41]
	v_mfma_f32_16x16x32_bf16 v[30:33], v[172:175], v[190:193], v[30:33]
	v_mfma_f32_16x16x32_bf16 v[22:25], v[164:167], v[206:209], v[22:25]
	v_mfma_f32_16x16x32_bf16 v[14:17], v[172:175], v[206:209], v[14:17]
	v_mfma_f32_16x16x32_bf16 v[6:9], v[164:167], v[214:217], v[6:9]
	v_mfma_f32_16x16x32_bf16 v[2:5], v[172:175], v[214:217], v[2:5]
	s_barrier
	s_setprio 0
	s_add_i32 s46, 0, 0x18000
	s_add_i32 s47, 0, 0x1c000
	v_add_u32_e32 v142, s46, v188
	v_add_u32_e32 v172, s47, v188
	ds_read_b128 v[130:133], v142
	ds_read_b128 v[134:137], v142 offset:1024
	ds_read_b128 v[138:141], v142 offset:2048
	ds_read_b128 v[142:145], v142 offset:3072
	ds_read_b128 v[146:149], v172
	ds_read_b128 v[164:167], v172 offset:1024
	ds_read_b128 v[168:171], v172 offset:2048
	ds_read_b128 v[172:175], v172 offset:3072
	s_add_u32 s0, s50, 0x158000
	s_addc_u32 s1, s51, 0
	s_mov_b32 m0, s31
	v_lshl_add_u64 v[224:225], s[0:1], 0, v[150:151]
	ds_read_b128 v[176:179], v189 offset:32768
	ds_read_b128 v[180:183], v189 offset:33792
	ds_read_b128 v[184:187], v189 offset:34816
	ds_read_b128 v[190:193], v189 offset:35840
	ds_read_b128 v[202:205], v189 offset:36864
	ds_read_b128 v[206:209], v189 offset:37888
	ds_read_b128 v[210:213], v189 offset:38912
	ds_read_b128 v[214:217], v189 offset:39936
	global_load_lds_dwordx4 v[224:225], off
	v_lshl_add_u64 v[224:225], s[0:1], 0, v[152:153]
	s_mov_b32 m0, s34
	s_nop 0
	global_load_lds_dwordx4 v[224:225], off
	s_waitcnt vmcnt(8)
	s_waitcnt lgkmcnt(0)
	s_setprio 1
	s_barrier
	v_mfma_f32_16x16x32_bf16 v[126:129], v[130:133], v[176:179], v[126:129]
	v_mfma_f32_16x16x32_bf16 v[122:125], v[138:141], v[176:179], v[122:125]
	v_mfma_f32_16x16x32_bf16 v[110:113], v[130:133], v[184:187], v[110:113]
	v_mfma_f32_16x16x32_bf16 v[106:109], v[138:141], v[184:187], v[106:109]
	v_mfma_f32_16x16x32_bf16 v[98:101], v[130:133], v[202:205], v[98:101]
	v_mfma_f32_16x16x32_bf16 v[90:93], v[138:141], v[202:205], v[90:93]
	v_mfma_f32_16x16x32_bf16 v[82:85], v[130:133], v[210:213], v[82:85]
	v_mfma_f32_16x16x32_bf16 v[74:77], v[138:141], v[210:213], v[74:77]
	v_mfma_f32_16x16x32_bf16 v[126:129], v[134:137], v[180:183], v[126:129]
	v_mfma_f32_16x16x32_bf16 v[122:125], v[142:145], v[180:183], v[122:125]
	v_mfma_f32_16x16x32_bf16 v[110:113], v[134:137], v[190:193], v[110:113]
	v_mfma_f32_16x16x32_bf16 v[106:109], v[142:145], v[190:193], v[106:109]
	v_mfma_f32_16x16x32_bf16 v[98:101], v[134:137], v[206:209], v[98:101]
	v_mfma_f32_16x16x32_bf16 v[90:93], v[142:145], v[206:209], v[90:93]
	v_mfma_f32_16x16x32_bf16 v[82:85], v[134:137], v[214:217], v[82:85]
	v_mfma_f32_16x16x32_bf16 v[74:77], v[142:145], v[214:217], v[74:77]
	v_mfma_f32_16x16x32_bf16 v[118:121], v[146:149], v[176:179], v[118:121]
	v_mfma_f32_16x16x32_bf16 v[114:117], v[168:171], v[176:179], v[114:117]
	v_mfma_f32_16x16x32_bf16 v[102:105], v[146:149], v[184:187], v[102:105]
	v_mfma_f32_16x16x32_bf16 v[94:97], v[168:171], v[184:187], v[94:97]
	v_mfma_f32_16x16x32_bf16 v[86:89], v[146:149], v[202:205], v[86:89]
	v_mfma_f32_16x16x32_bf16 v[78:81], v[168:171], v[202:205], v[78:81]
	v_mfma_f32_16x16x32_bf16 v[70:73], v[146:149], v[210:213], v[70:73]
	v_mfma_f32_16x16x32_bf16 v[66:69], v[168:171], v[210:213], v[66:69]
	v_mfma_f32_16x16x32_bf16 v[118:121], v[164:167], v[180:183], v[118:121]
	v_mfma_f32_16x16x32_bf16 v[114:117], v[172:175], v[180:183], v[114:117]
	v_mfma_f32_16x16x32_bf16 v[102:105], v[164:167], v[190:193], v[102:105]
	v_mfma_f32_16x16x32_bf16 v[94:97], v[172:175], v[190:193], v[94:97]
	v_mfma_f32_16x16x32_bf16 v[86:89], v[164:167], v[206:209], v[86:89]
	v_mfma_f32_16x16x32_bf16 v[78:81], v[172:175], v[206:209], v[78:81]
	v_mfma_f32_16x16x32_bf16 v[70:73], v[164:167], v[214:217], v[70:73]
	v_mfma_f32_16x16x32_bf16 v[66:69], v[172:175], v[214:217], v[66:69]
	s_barrier
	s_setprio 0
	s_add_i32 s0, s46, s26
	v_lshl_add_u64 v[194:195], v[194:195], 0, s[16:17]
	s_mov_b32 m0, s0
	ds_read_b128 v[176:179], v189 offset:49152
	ds_read_b128 v[180:183], v189 offset:50176
	ds_read_b128 v[184:187], v189 offset:51200
	ds_read_b128 v[190:193], v189 offset:52224
	ds_read_b128 v[202:205], v189 offset:53248
	ds_read_b128 v[206:209], v189 offset:54272
	ds_read_b128 v[210:213], v189 offset:55296
	ds_read_b128 v[214:217], v189 offset:56320
	global_load_lds_dwordx4 v[194:195], off
	s_add_i32 m0, s0, 0x2000
	s_add_u32 s0, s48, 0x158080
	v_lshl_add_u64 v[194:195], v[218:219], 0, s[16:17]
	s_addc_u32 s1, s49, 0
	s_add_i32 s46, s47, s26
	global_load_lds_dwordx4 v[194:195], off
	v_lshl_add_u64 v[194:195], s[0:1], 0, v[196:197]
	s_mov_b32 m0, s46
	s_nop 0
	global_load_lds_dwordx4 v[194:195], off
	v_lshl_add_u64 v[194:195], s[0:1], 0, v[154:155]
	s_add_i32 m0, s46, 0x2000
	s_nop 0
	global_load_lds_dwordx4 v[194:195], off
	v_lshl_add_u64 v[194:195], v[220:221], 0, s[16:17]
	s_mov_b32 m0, s53
	s_nop 0
	global_load_lds_dwordx4 v[194:195], off
	v_lshl_add_u64 v[194:195], v[222:223], 0, s[16:17]
	s_mov_b32 m0, s58
	s_nop 0
	global_load_lds_dwordx4 v[194:195], off
	s_waitcnt vmcnt(8)
	s_waitcnt lgkmcnt(0)
	s_setprio 1
	s_barrier
	v_mfma_f32_16x16x32_bf16 v[62:65], v[130:133], v[176:179], v[62:65]
	v_mfma_f32_16x16x32_bf16 v[58:61], v[138:141], v[176:179], v[58:61]
	v_mfma_f32_16x16x32_bf16 v[50:53], v[130:133], v[184:187], v[50:53]
	v_mfma_f32_16x16x32_bf16 v[42:45], v[138:141], v[184:187], v[42:45]
	v_mfma_f32_16x16x32_bf16 v[34:37], v[130:133], v[202:205], v[34:37]
	v_mfma_f32_16x16x32_bf16 v[26:29], v[138:141], v[202:205], v[26:29]
	v_mfma_f32_16x16x32_bf16 v[18:21], v[130:133], v[210:213], v[18:21]
	v_mfma_f32_16x16x32_bf16 v[10:13], v[138:141], v[210:213], v[10:13]
	v_mfma_f32_16x16x32_bf16 v[62:65], v[134:137], v[180:183], v[62:65]
	v_mfma_f32_16x16x32_bf16 v[58:61], v[142:145], v[180:183], v[58:61]
	v_mfma_f32_16x16x32_bf16 v[50:53], v[134:137], v[190:193], v[50:53]
	v_mfma_f32_16x16x32_bf16 v[42:45], v[142:145], v[190:193], v[42:45]
	v_mfma_f32_16x16x32_bf16 v[34:37], v[134:137], v[206:209], v[34:37]
	v_mfma_f32_16x16x32_bf16 v[26:29], v[142:145], v[206:209], v[26:29]
	v_mfma_f32_16x16x32_bf16 v[18:21], v[134:137], v[214:217], v[18:21]
	v_mfma_f32_16x16x32_bf16 v[10:13], v[142:145], v[214:217], v[10:13]
	v_mfma_f32_16x16x32_bf16 v[54:57], v[146:149], v[176:179], v[54:57]
	v_mfma_f32_16x16x32_bf16 v[46:49], v[168:171], v[176:179], v[46:49]
	v_mfma_f32_16x16x32_bf16 v[38:41], v[146:149], v[184:187], v[38:41]
	v_mfma_f32_16x16x32_bf16 v[30:33], v[168:171], v[184:187], v[30:33]
	v_mfma_f32_16x16x32_bf16 v[22:25], v[146:149], v[202:205], v[22:25]
	v_mfma_f32_16x16x32_bf16 v[14:17], v[168:171], v[202:205], v[14:17]
	v_mfma_f32_16x16x32_bf16 v[6:9], v[146:149], v[210:213], v[6:9]
	v_mfma_f32_16x16x32_bf16 v[2:5], v[168:171], v[210:213], v[2:5]
	v_mfma_f32_16x16x32_bf16 v[54:57], v[164:167], v[180:183], v[54:57]
	v_mfma_f32_16x16x32_bf16 v[46:49], v[172:175], v[180:183], v[46:49]
	v_mfma_f32_16x16x32_bf16 v[38:41], v[164:167], v[190:193], v[38:41]
	v_mfma_f32_16x16x32_bf16 v[30:33], v[172:175], v[190:193], v[30:33]
	v_mfma_f32_16x16x32_bf16 v[22:25], v[164:167], v[206:209], v[22:25]
	v_mfma_f32_16x16x32_bf16 v[14:17], v[172:175], v[206:209], v[14:17]
	v_mfma_f32_16x16x32_bf16 v[6:9], v[164:167], v[214:217], v[6:9]
	v_mfma_f32_16x16x32_bf16 v[2:5], v[172:175], v[214:217], v[2:5]
	s_barrier
	s_setprio 0
	s_add_u32 s70, s70, 0x100
	s_addc_u32 s71, s71, 0
	s_cmp_ge_i32 s72, s69
	s_mov_b64 s[46:47], s[8:9]
	s_mov_b32 s48, s72
	s_cbranch_scc0 .LBB0_2588
	s_and_b64 vcc, exec, s[28:29]
	s_cbranch_vccz .LBB0_2591
	s_barrier
